# v77 plus comb gain multiplies fill DPP wait states and P6 epilogue q written directly by fmamk
# baseline (speedup 1.0000x reference)
.Lcomb:
	s_mov_b64 exec, -1
	v_lshlrev_b32_e32 v132, 5, v240
	v_lshlrev_b32_e32 v128, 4, v240
	global_load_dwordx4 v[120:123], v132, s[62:63]
	global_load_dwordx4 v[124:127], v132, s[62:63] offset:16
	s_lshl_b32 s98, s74, 10
	v_add_u32_e32 v133, s98, v128
	s_mul_i32 s98, s74, 0xe00
	s_addk_i32 s98, 0xa00
	v_add_u32_e32 v134, s98, v128
	s_lshl_b32 s98, s74, 11
	s_addk_i32 s98, 0x400
	v_add_u32_e32 v135, s98, v128
	v_mov_b32_e32 v140, 0xbdd2d3e8
	v_mov_b32_e32 v142, 0xc0135761
	v_mov_b32_e32 v131, 0x358637bd
	global_load_dwordx4 v[0:3], v133, s[22:23] nt
	global_load_dwordx4 v[4:7], v133, s[20:21] nt
	global_load_dwordx4 v[8:11], v134, s[38:39] nt
	v_add_u32_e32 v136, 0x200000, v133
	v_add_u32_e32 v137, 0x700000, v134
	global_load_dwordx4 v[12:15], v136, s[22:23] nt
	global_load_dwordx4 v[16:19], v136, s[20:21] nt
	global_load_dwordx4 v[20:23], v137, s[38:39] nt
	v_add_u32_e32 v136, 0x400000, v133
	v_add_u32_e32 v137, 0xe00000, v134
	global_load_dwordx4 v[24:27], v136, s[22:23] nt
	global_load_dwordx4 v[28:31], v136, s[20:21] nt
	global_load_dwordx4 v[32:35], v137, s[38:39] nt
	v_add_u32_e32 v136, 0x600000, v133
	v_add_u32_e32 v137, 0x1500000, v134
	global_load_dwordx4 v[36:39], v136, s[22:23] nt
	global_load_dwordx4 v[40:43], v136, s[20:21] nt
	global_load_dwordx4 v[44:47], v137, s[38:39] nt
	v_add_u32_e32 v136, 0x800000, v133
	v_add_u32_e32 v137, 0x1c00000, v134
	global_load_dwordx4 v[48:51], v136, s[22:23] nt
	global_load_dwordx4 v[52:55], v136, s[20:21] nt
	global_load_dwordx4 v[56:59], v137, s[38:39] nt
	v_add_u32_e32 v136, 0xa00000, v133
	v_add_u32_e32 v137, 0x2300000, v134
	global_load_dwordx4 v[60:63], v136, s[22:23] nt
	global_load_dwordx4 v[64:67], v136, s[20:21] nt
	global_load_dwordx4 v[68:71], v137, s[38:39] nt
	v_add_u32_e32 v136, 0xc00000, v133
	v_add_u32_e32 v137, 0x2a00000, v134
	global_load_dwordx4 v[72:75], v136, s[22:23] nt
	global_load_dwordx4 v[76:79], v136, s[20:21] nt
	global_load_dwordx4 v[80:83], v137, s[38:39] nt
	v_add_u32_e32 v136, 0xe00000, v133
	v_add_u32_e32 v137, 0x3100000, v134
	global_load_dwordx4 v[84:87], v136, s[22:23] nt
	global_load_dwordx4 v[88:91], v136, s[20:21] nt
	global_load_dwordx4 v[92:95], v137, s[38:39] nt
	s_waitcnt vmcnt(21)
	v_lshlrev_b32_e32 v146, 16, v0
	v_and_b32_e32 v147, 0xffff0000, v0
	v_lshlrev_b32_e32 v148, 16, v1
	v_and_b32_e32 v149, 0xffff0000, v1
	v_lshlrev_b32_e32 v150, 16, v2
	v_and_b32_e32 v151, 0xffff0000, v2
	v_lshlrev_b32_e32 v152, 16, v3
	v_and_b32_e32 v153, 0xffff0000, v3
	v_lshlrev_b32_e32 v154, 16, v4
	v_and_b32_e32 v155, 0xffff0000, v4
	v_lshlrev_b32_e32 v156, 16, v5
	v_and_b32_e32 v157, 0xffff0000, v5
	v_lshlrev_b32_e32 v158, 16, v6
	v_and_b32_e32 v159, 0xffff0000, v6
	v_lshlrev_b32_e32 v160, 16, v7
	v_and_b32_e32 v161, 0xffff0000, v7
	v_lshlrev_b32_e32 v162, 16, v8
	v_and_b32_e32 v163, 0xffff0000, v8
	v_lshlrev_b32_e32 v164, 16, v9
	v_and_b32_e32 v165, 0xffff0000, v9
	v_lshlrev_b32_e32 v166, 16, v10
	v_and_b32_e32 v167, 0xffff0000, v10
	v_lshlrev_b32_e32 v168, 16, v11
	v_and_b32_e32 v169, 0xffff0000, v11
	v_pk_add_f32 v[146:147], v[146:147], v[154:155]
	v_pk_add_f32 v[148:149], v[148:149], v[156:157]
	v_pk_add_f32 v[150:151], v[150:151], v[158:159]
	v_pk_add_f32 v[152:153], v[152:153], v[160:161]
	v_pk_mul_f32 v[170:171], v[162:163], v[162:163]
	v_pk_mul_f32 v[172:173], v[164:165], v[164:165]
	v_pk_mul_f32 v[174:175], v[166:167], v[166:167]
	v_pk_mul_f32 v[176:177], v[168:169], v[168:169]
	v_pk_fma_f32 v[170:171], v[170:171], v[140:141], v[142:143] op_sel_hi:[1,0,0]
	v_pk_fma_f32 v[172:173], v[172:173], v[140:141], v[142:143] op_sel_hi:[1,0,0]
	v_pk_fma_f32 v[174:175], v[174:175], v[140:141], v[142:143] op_sel_hi:[1,0,0]
	v_pk_fma_f32 v[176:177], v[176:177], v[140:141], v[142:143] op_sel_hi:[1,0,0]
	v_pk_mul_f32 v[170:171], v[170:171], v[162:163]
	v_pk_mul_f32 v[172:173], v[172:173], v[164:165]
	v_pk_mul_f32 v[174:175], v[174:175], v[166:167]
	v_pk_mul_f32 v[176:177], v[176:177], v[168:169]
	v_pk_mul_f32 v[154:155], v[146:147], v[162:163]
	v_pk_mul_f32 v[156:157], v[148:149], v[164:165]
	v_pk_mul_f32 v[158:159], v[150:151], v[166:167]
	v_pk_mul_f32 v[160:161], v[152:153], v[168:169]
	v_exp_f32_e32 v170, v170
	v_exp_f32_e32 v171, v171
	v_exp_f32_e32 v172, v172
	v_exp_f32_e32 v173, v173
	v_exp_f32_e32 v174, v174
	v_exp_f32_e32 v175, v175
	v_exp_f32_e32 v176, v176
	v_exp_f32_e32 v177, v177
	v_pk_add_f32 v[170:171], v[170:171], 1.0 op_sel_hi:[1,0]
	v_pk_add_f32 v[172:173], v[172:173], 1.0 op_sel_hi:[1,0]
	v_pk_add_f32 v[174:175], v[174:175], 1.0 op_sel_hi:[1,0]
	v_pk_add_f32 v[176:177], v[176:177], 1.0 op_sel_hi:[1,0]
	v_rcp_f32_e32 v170, v170
	v_rcp_f32_e32 v171, v171
	v_rcp_f32_e32 v172, v172
	v_rcp_f32_e32 v173, v173
	v_rcp_f32_e32 v174, v174
	v_rcp_f32_e32 v175, v175
	v_rcp_f32_e32 v176, v176
	v_rcp_f32_e32 v177, v177
	v_pk_mul_f32 v[96:97], v[154:155], v[170:171]
	v_pk_mul_f32 v[98:99], v[156:157], v[172:173]
	v_pk_mul_f32 v[100:101], v[158:159], v[174:175]
	v_pk_mul_f32 v[102:103], v[160:161], v[176:177]
	v_pk_mul_f32 v[112:113], v[96:97], v[96:97]
	v_pk_mul_f32 v[114:115], v[98:99], v[98:99]
	v_pk_fma_f32 v[112:113], v[100:101], v[100:101], v[112:113]
	v_pk_fma_f32 v[114:115], v[102:103], v[102:103], v[114:115]
	v_pk_add_f32 v[112:113], v[112:113], v[114:115]
	v_add_f32_e32 v112, v112, v113
	v_pk_mul_f32 v[146:147], v[96:97], v[120:121]
	v_pk_mul_f32 v[148:149], v[98:99], v[122:123]
	v_add_f32_dpp v112, v112, v112 quad_perm:[1,0,3,2] row_mask:0xf bank_mask:0xf
	v_pk_mul_f32 v[150:151], v[100:101], v[124:125]
	v_pk_mul_f32 v[152:153], v[102:103], v[126:127]
	v_add_f32_dpp v112, v112, v112 quad_perm:[2,3,0,1] row_mask:0xf bank_mask:0xf
	s_nop 1
	v_add_f32_dpp v112, v112, v112 row_half_mirror row_mask:0xf bank_mask:0xf
	s_nop 1
	v_add_f32_dpp v112, v112, v112 row_mirror row_mask:0xf bank_mask:0xf
	s_nop 1
	v_readlane_b32 s98, v112, 0
	v_readlane_b32 s99, v112, 16
	v_readlane_b32 s100, v112, 32
	v_readlane_b32 vcc_lo, v112, 48
	s_nop 1
	v_mov_b32_e32 v113, s98
	v_add_f32_e32 v113, s99, v113
	v_add_f32_e32 v113, s100, v113
	v_add_f32_e32 v113, vcc_lo, v113
	v_fmamk_f32 v144, v113, 0x3b000000, v131
	v_rsq_f32_e32 v144, v144
	s_nop 0
	v_pk_mul_f32 v[146:147], v[146:147], v[144:145] op_sel_hi:[1,0]
	v_pk_mul_f32 v[148:149], v[148:149], v[144:145] op_sel_hi:[1,0]
	v_pk_mul_f32 v[150:151], v[150:151], v[144:145] op_sel_hi:[1,0]
	v_pk_mul_f32 v[152:153], v[152:153], v[144:145] op_sel_hi:[1,0]
	v_cvt_pk_bf16_f32 v116, v146, v147
	v_cvt_pk_bf16_f32 v117, v148, v149
	v_cvt_pk_bf16_f32 v118, v150, v151
	v_cvt_pk_bf16_f32 v119, v152, v153
	global_store_dwordx4 v135, v[116:119], s[34:35]
	v_add_u32_e32 v136, 0x1000000, v133
	v_add_u32_e32 v137, 0x3800000, v134
	global_load_dwordx4 v[0:3], v136, s[22:23] nt
	global_load_dwordx4 v[4:7], v136, s[20:21] nt
	global_load_dwordx4 v[8:11], v137, s[38:39] nt
	s_waitcnt vmcnt(22)
	v_lshlrev_b32_e32 v146, 16, v12
	v_and_b32_e32 v147, 0xffff0000, v12
	v_lshlrev_b32_e32 v148, 16, v13
	v_and_b32_e32 v149, 0xffff0000, v13
	v_lshlrev_b32_e32 v150, 16, v14
	v_and_b32_e32 v151, 0xffff0000, v14
	v_lshlrev_b32_e32 v152, 16, v15
	v_and_b32_e32 v153, 0xffff0000, v15
	v_lshlrev_b32_e32 v154, 16, v16
	v_and_b32_e32 v155, 0xffff0000, v16
	v_lshlrev_b32_e32 v156, 16, v17
	v_and_b32_e32 v157, 0xffff0000, v17
	v_lshlrev_b32_e32 v158, 16, v18
	v_and_b32_e32 v159, 0xffff0000, v18
	v_lshlrev_b32_e32 v160, 16, v19
	v_and_b32_e32 v161, 0xffff0000, v19
	v_lshlrev_b32_e32 v162, 16, v20
	v_and_b32_e32 v163, 0xffff0000, v20
	v_lshlrev_b32_e32 v164, 16, v21
	v_and_b32_e32 v165, 0xffff0000, v21
	v_lshlrev_b32_e32 v166, 16, v22
	v_and_b32_e32 v167, 0xffff0000, v22
	v_lshlrev_b32_e32 v168, 16, v23
	v_and_b32_e32 v169, 0xffff0000, v23
	v_pk_add_f32 v[146:147], v[146:147], v[154:155]
	v_pk_add_f32 v[148:149], v[148:149], v[156:157]
	v_pk_add_f32 v[150:151], v[150:151], v[158:159]
	v_pk_add_f32 v[152:153], v[152:153], v[160:161]
	v_pk_mul_f32 v[170:171], v[162:163], v[162:163]
	v_pk_mul_f32 v[172:173], v[164:165], v[164:165]
	v_pk_mul_f32 v[174:175], v[166:167], v[166:167]
	v_pk_mul_f32 v[176:177], v[168:169], v[168:169]
	v_pk_fma_f32 v[170:171], v[170:171], v[140:141], v[142:143] op_sel_hi:[1,0,0]
	v_pk_fma_f32 v[172:173], v[172:173], v[140:141], v[142:143] op_sel_hi:[1,0,0]
	v_pk_fma_f32 v[174:175], v[174:175], v[140:141], v[142:143] op_sel_hi:[1,0,0]
	v_pk_fma_f32 v[176:177], v[176:177], v[140:141], v[142:143] op_sel_hi:[1,0,0]
	v_pk_mul_f32 v[170:171], v[170:171], v[162:163]
	v_pk_mul_f32 v[172:173], v[172:173], v[164:165]
	v_pk_mul_f32 v[174:175], v[174:175], v[166:167]
	v_pk_mul_f32 v[176:177], v[176:177], v[168:169]
	v_pk_mul_f32 v[154:155], v[146:147], v[162:163]
	v_pk_mul_f32 v[156:157], v[148:149], v[164:165]
	v_pk_mul_f32 v[158:159], v[150:151], v[166:167]
	v_pk_mul_f32 v[160:161], v[152:153], v[168:169]
	v_exp_f32_e32 v170, v170
	v_exp_f32_e32 v171, v171
	v_exp_f32_e32 v172, v172
	v_exp_f32_e32 v173, v173
	v_exp_f32_e32 v174, v174
	v_exp_f32_e32 v175, v175
	v_exp_f32_e32 v176, v176
	v_exp_f32_e32 v177, v177
	v_pk_add_f32 v[170:171], v[170:171], 1.0 op_sel_hi:[1,0]
	v_pk_add_f32 v[172:173], v[172:173], 1.0 op_sel_hi:[1,0]
	v_pk_add_f32 v[174:175], v[174:175], 1.0 op_sel_hi:[1,0]
	v_pk_add_f32 v[176:177], v[176:177], 1.0 op_sel_hi:[1,0]
	v_rcp_f32_e32 v170, v170
	v_rcp_f32_e32 v171, v171
	v_rcp_f32_e32 v172, v172
	v_rcp_f32_e32 v173, v173
	v_rcp_f32_e32 v174, v174
	v_rcp_f32_e32 v175, v175
	v_rcp_f32_e32 v176, v176
	v_rcp_f32_e32 v177, v177
	v_pk_mul_f32 v[96:97], v[154:155], v[170:171]
	v_pk_mul_f32 v[98:99], v[156:157], v[172:173]
	v_pk_mul_f32 v[100:101], v[158:159], v[174:175]
	v_pk_mul_f32 v[102:103], v[160:161], v[176:177]
	v_pk_mul_f32 v[112:113], v[96:97], v[96:97]
	v_pk_mul_f32 v[114:115], v[98:99], v[98:99]
	v_pk_fma_f32 v[112:113], v[100:101], v[100:101], v[112:113]
	v_pk_fma_f32 v[114:115], v[102:103], v[102:103], v[114:115]
	v_pk_add_f32 v[112:113], v[112:113], v[114:115]
	v_add_f32_e32 v112, v112, v113
	v_pk_mul_f32 v[146:147], v[96:97], v[120:121]
	v_pk_mul_f32 v[148:149], v[98:99], v[122:123]
	v_add_f32_dpp v112, v112, v112 quad_perm:[1,0,3,2] row_mask:0xf bank_mask:0xf
	v_pk_mul_f32 v[150:151], v[100:101], v[124:125]
	v_pk_mul_f32 v[152:153], v[102:103], v[126:127]
	v_add_f32_dpp v112, v112, v112 quad_perm:[2,3,0,1] row_mask:0xf bank_mask:0xf
	s_nop 1
	v_add_f32_dpp v112, v112, v112 row_half_mirror row_mask:0xf bank_mask:0xf
	s_nop 1
	v_add_f32_dpp v112, v112, v112 row_mirror row_mask:0xf bank_mask:0xf
	s_nop 1
	v_readlane_b32 s98, v112, 0
	v_readlane_b32 s99, v112, 16
	v_readlane_b32 s100, v112, 32
	v_readlane_b32 vcc_lo, v112, 48
	s_nop 1
	v_mov_b32_e32 v113, s98
	v_add_f32_e32 v113, s99, v113
	v_add_f32_e32 v113, s100, v113
	v_add_f32_e32 v113, vcc_lo, v113
	v_fmamk_f32 v144, v113, 0x3b000000, v131
	v_rsq_f32_e32 v144, v144
	s_nop 0
	v_pk_mul_f32 v[146:147], v[146:147], v[144:145] op_sel_hi:[1,0]
	v_pk_mul_f32 v[148:149], v[148:149], v[144:145] op_sel_hi:[1,0]
	v_pk_mul_f32 v[150:151], v[150:151], v[144:145] op_sel_hi:[1,0]
	v_pk_mul_f32 v[152:153], v[152:153], v[144:145] op_sel_hi:[1,0]
	v_cvt_pk_bf16_f32 v116, v146, v147
	v_cvt_pk_bf16_f32 v117, v148, v149
	v_cvt_pk_bf16_f32 v118, v150, v151
	v_cvt_pk_bf16_f32 v119, v152, v153
	v_add_u32_e32 v138, 0x400000, v135
	global_store_dwordx4 v138, v[116:119], s[34:35]
	v_add_u32_e32 v136, 0x1200000, v133
	v_add_u32_e32 v137, 0x3f00000, v134
	global_load_dwordx4 v[12:15], v136, s[22:23] nt
	global_load_dwordx4 v[16:19], v136, s[20:21] nt
	global_load_dwordx4 v[20:23], v137, s[38:39] nt
	s_waitcnt vmcnt(23)
	v_lshlrev_b32_e32 v146, 16, v24
	v_and_b32_e32 v147, 0xffff0000, v24
	v_lshlrev_b32_e32 v148, 16, v25
	v_and_b32_e32 v149, 0xffff0000, v25
	v_lshlrev_b32_e32 v150, 16, v26
	v_and_b32_e32 v151, 0xffff0000, v26
	v_lshlrev_b32_e32 v152, 16, v27
	v_and_b32_e32 v153, 0xffff0000, v27
	v_lshlrev_b32_e32 v154, 16, v28
	v_and_b32_e32 v155, 0xffff0000, v28
	v_lshlrev_b32_e32 v156, 16, v29
	v_and_b32_e32 v157, 0xffff0000, v29
	v_lshlrev_b32_e32 v158, 16, v30
	v_and_b32_e32 v159, 0xffff0000, v30
	v_lshlrev_b32_e32 v160, 16, v31
	v_and_b32_e32 v161, 0xffff0000, v31
	v_lshlrev_b32_e32 v162, 16, v32
	v_and_b32_e32 v163, 0xffff0000, v32
	v_lshlrev_b32_e32 v164, 16, v33
	v_and_b32_e32 v165, 0xffff0000, v33
	v_lshlrev_b32_e32 v166, 16, v34
	v_and_b32_e32 v167, 0xffff0000, v34
	v_lshlrev_b32_e32 v168, 16, v35
	v_and_b32_e32 v169, 0xffff0000, v35
	v_pk_add_f32 v[146:147], v[146:147], v[154:155]
	v_pk_add_f32 v[148:149], v[148:149], v[156:157]
	v_pk_add_f32 v[150:151], v[150:151], v[158:159]
	v_pk_add_f32 v[152:153], v[152:153], v[160:161]
	v_pk_mul_f32 v[170:171], v[162:163], v[162:163]
	v_pk_mul_f32 v[172:173], v[164:165], v[164:165]
	v_pk_mul_f32 v[174:175], v[166:167], v[166:167]
	v_pk_mul_f32 v[176:177], v[168:169], v[168:169]
	v_pk_fma_f32 v[170:171], v[170:171], v[140:141], v[142:143] op_sel_hi:[1,0,0]
	v_pk_fma_f32 v[172:173], v[172:173], v[140:141], v[142:143] op_sel_hi:[1,0,0]
	v_pk_fma_f32 v[174:175], v[174:175], v[140:141], v[142:143] op_sel_hi:[1,0,0]
	v_pk_fma_f32 v[176:177], v[176:177], v[140:141], v[142:143] op_sel_hi:[1,0,0]
	v_pk_mul_f32 v[170:171], v[170:171], v[162:163]
	v_pk_mul_f32 v[172:173], v[172:173], v[164:165]
	v_pk_mul_f32 v[174:175], v[174:175], v[166:167]
	v_pk_mul_f32 v[176:177], v[176:177], v[168:169]
	v_pk_mul_f32 v[154:155], v[146:147], v[162:163]
	v_pk_mul_f32 v[156:157], v[148:149], v[164:165]
	v_pk_mul_f32 v[158:159], v[150:151], v[166:167]
	v_pk_mul_f32 v[160:161], v[152:153], v[168:169]
	v_exp_f32_e32 v170, v170
	v_exp_f32_e32 v171, v171
	v_exp_f32_e32 v172, v172
	v_exp_f32_e32 v173, v173
	v_exp_f32_e32 v174, v174
	v_exp_f32_e32 v175, v175
	v_exp_f32_e32 v176, v176
	v_exp_f32_e32 v177, v177
	v_pk_add_f32 v[170:171], v[170:171], 1.0 op_sel_hi:[1,0]
	v_pk_add_f32 v[172:173], v[172:173], 1.0 op_sel_hi:[1,0]
	v_pk_add_f32 v[174:175], v[174:175], 1.0 op_sel_hi:[1,0]
	v_pk_add_f32 v[176:177], v[176:177], 1.0 op_sel_hi:[1,0]
	v_rcp_f32_e32 v170, v170
	v_rcp_f32_e32 v171, v171
	v_rcp_f32_e32 v172, v172
	v_rcp_f32_e32 v173, v173
	v_rcp_f32_e32 v174, v174
	v_rcp_f32_e32 v175, v175
	v_rcp_f32_e32 v176, v176
	v_rcp_f32_e32 v177, v177
	v_pk_mul_f32 v[96:97], v[154:155], v[170:171]
	v_pk_mul_f32 v[98:99], v[156:157], v[172:173]
	v_pk_mul_f32 v[100:101], v[158:159], v[174:175]
	v_pk_mul_f32 v[102:103], v[160:161], v[176:177]
	v_pk_mul_f32 v[112:113], v[96:97], v[96:97]
	v_pk_mul_f32 v[114:115], v[98:99], v[98:99]
	v_pk_fma_f32 v[112:113], v[100:101], v[100:101], v[112:113]
	v_pk_fma_f32 v[114:115], v[102:103], v[102:103], v[114:115]
	v_pk_add_f32 v[112:113], v[112:113], v[114:115]
	v_add_f32_e32 v112, v112, v113
	v_pk_mul_f32 v[146:147], v[96:97], v[120:121]
	v_pk_mul_f32 v[148:149], v[98:99], v[122:123]
	v_add_f32_dpp v112, v112, v112 quad_perm:[1,0,3,2] row_mask:0xf bank_mask:0xf
	v_pk_mul_f32 v[150:151], v[100:101], v[124:125]
	v_pk_mul_f32 v[152:153], v[102:103], v[126:127]
	v_add_f32_dpp v112, v112, v112 quad_perm:[2,3,0,1] row_mask:0xf bank_mask:0xf
	s_nop 1
	v_add_f32_dpp v112, v112, v112 row_half_mirror row_mask:0xf bank_mask:0xf
	s_nop 1
	v_add_f32_dpp v112, v112, v112 row_mirror row_mask:0xf bank_mask:0xf
	s_nop 1
	v_readlane_b32 s98, v112, 0
	v_readlane_b32 s99, v112, 16
	v_readlane_b32 s100, v112, 32
	v_readlane_b32 vcc_lo, v112, 48
	s_nop 1
	v_mov_b32_e32 v113, s98
	v_add_f32_e32 v113, s99, v113
	v_add_f32_e32 v113, s100, v113
	v_add_f32_e32 v113, vcc_lo, v113
	v_fmamk_f32 v144, v113, 0x3b000000, v131
	v_rsq_f32_e32 v144, v144
	s_nop 0
	v_pk_mul_f32 v[146:147], v[146:147], v[144:145] op_sel_hi:[1,0]
	v_pk_mul_f32 v[148:149], v[148:149], v[144:145] op_sel_hi:[1,0]
	v_pk_mul_f32 v[150:151], v[150:151], v[144:145] op_sel_hi:[1,0]
	v_pk_mul_f32 v[152:153], v[152:153], v[144:145] op_sel_hi:[1,0]
	v_cvt_pk_bf16_f32 v116, v146, v147
	v_cvt_pk_bf16_f32 v117, v148, v149
	v_cvt_pk_bf16_f32 v118, v150, v151
	v_cvt_pk_bf16_f32 v119, v152, v153
	v_add_u32_e32 v138, 0x800000, v135
	global_store_dwordx4 v138, v[116:119], s[34:35]
	v_add_u32_e32 v136, 0x1400000, v133
	v_add_u32_e32 v137, 0x4600000, v134
	global_load_dwordx4 v[24:27], v136, s[22:23] nt
	global_load_dwordx4 v[28:31], v136, s[20:21] nt
	global_load_dwordx4 v[32:35], v137, s[38:39] nt
	s_waitcnt vmcnt(24)
	v_lshlrev_b32_e32 v146, 16, v36
	v_and_b32_e32 v147, 0xffff0000, v36
	v_lshlrev_b32_e32 v148, 16, v37
	v_and_b32_e32 v149, 0xffff0000, v37
	v_lshlrev_b32_e32 v150, 16, v38
	v_and_b32_e32 v151, 0xffff0000, v38
	v_lshlrev_b32_e32 v152, 16, v39
	v_and_b32_e32 v153, 0xffff0000, v39
	v_lshlrev_b32_e32 v154, 16, v40
	v_and_b32_e32 v155, 0xffff0000, v40
	v_lshlrev_b32_e32 v156, 16, v41
	v_and_b32_e32 v157, 0xffff0000, v41
	v_lshlrev_b32_e32 v158, 16, v42
	v_and_b32_e32 v159, 0xffff0000, v42
	v_lshlrev_b32_e32 v160, 16, v43
	v_and_b32_e32 v161, 0xffff0000, v43
	v_lshlrev_b32_e32 v162, 16, v44
	v_and_b32_e32 v163, 0xffff0000, v44
	v_lshlrev_b32_e32 v164, 16, v45
	v_and_b32_e32 v165, 0xffff0000, v45
	v_lshlrev_b32_e32 v166, 16, v46
	v_and_b32_e32 v167, 0xffff0000, v46
	v_lshlrev_b32_e32 v168, 16, v47
	v_and_b32_e32 v169, 0xffff0000, v47
	v_pk_add_f32 v[146:147], v[146:147], v[154:155]
	v_pk_add_f32 v[148:149], v[148:149], v[156:157]
	v_pk_add_f32 v[150:151], v[150:151], v[158:159]
	v_pk_add_f32 v[152:153], v[152:153], v[160:161]
	v_pk_mul_f32 v[170:171], v[162:163], v[162:163]
	v_pk_mul_f32 v[172:173], v[164:165], v[164:165]
	v_pk_mul_f32 v[174:175], v[166:167], v[166:167]
	v_pk_mul_f32 v[176:177], v[168:169], v[168:169]
	v_pk_fma_f32 v[170:171], v[170:171], v[140:141], v[142:143] op_sel_hi:[1,0,0]
	v_pk_fma_f32 v[172:173], v[172:173], v[140:141], v[142:143] op_sel_hi:[1,0,0]
	v_pk_fma_f32 v[174:175], v[174:175], v[140:141], v[142:143] op_sel_hi:[1,0,0]
	v_pk_fma_f32 v[176:177], v[176:177], v[140:141], v[142:143] op_sel_hi:[1,0,0]
	v_pk_mul_f32 v[170:171], v[170:171], v[162:163]
	v_pk_mul_f32 v[172:173], v[172:173], v[164:165]
	v_pk_mul_f32 v[174:175], v[174:175], v[166:167]
	v_pk_mul_f32 v[176:177], v[176:177], v[168:169]
	v_pk_mul_f32 v[154:155], v[146:147], v[162:163]
	v_pk_mul_f32 v[156:157], v[148:149], v[164:165]
	v_pk_mul_f32 v[158:159], v[150:151], v[166:167]
	v_pk_mul_f32 v[160:161], v[152:153], v[168:169]
	v_exp_f32_e32 v170, v170
	v_exp_f32_e32 v171, v171
	v_exp_f32_e32 v172, v172
	v_exp_f32_e32 v173, v173
	v_exp_f32_e32 v174, v174
	v_exp_f32_e32 v175, v175
	v_exp_f32_e32 v176, v176
	v_exp_f32_e32 v177, v177
	v_pk_add_f32 v[170:171], v[170:171], 1.0 op_sel_hi:[1,0]
	v_pk_add_f32 v[172:173], v[172:173], 1.0 op_sel_hi:[1,0]
	v_pk_add_f32 v[174:175], v[174:175], 1.0 op_sel_hi:[1,0]
	v_pk_add_f32 v[176:177], v[176:177], 1.0 op_sel_hi:[1,0]
	v_rcp_f32_e32 v170, v170
	v_rcp_f32_e32 v171, v171
	v_rcp_f32_e32 v172, v172
	v_rcp_f32_e32 v173, v173
	v_rcp_f32_e32 v174, v174
	v_rcp_f32_e32 v175, v175
	v_rcp_f32_e32 v176, v176
	v_rcp_f32_e32 v177, v177
	v_pk_mul_f32 v[96:97], v[154:155], v[170:171]
	v_pk_mul_f32 v[98:99], v[156:157], v[172:173]
	v_pk_mul_f32 v[100:101], v[158:159], v[174:175]
	v_pk_mul_f32 v[102:103], v[160:161], v[176:177]
	v_pk_mul_f32 v[112:113], v[96:97], v[96:97]
	v_pk_mul_f32 v[114:115], v[98:99], v[98:99]
	v_pk_fma_f32 v[112:113], v[100:101], v[100:101], v[112:113]
	v_pk_fma_f32 v[114:115], v[102:103], v[102:103], v[114:115]
	v_pk_add_f32 v[112:113], v[112:113], v[114:115]
	v_add_f32_e32 v112, v112, v113
	v_pk_mul_f32 v[146:147], v[96:97], v[120:121]
	v_pk_mul_f32 v[148:149], v[98:99], v[122:123]
	v_add_f32_dpp v112, v112, v112 quad_perm:[1,0,3,2] row_mask:0xf bank_mask:0xf
	v_pk_mul_f32 v[150:151], v[100:101], v[124:125]
	v_pk_mul_f32 v[152:153], v[102:103], v[126:127]
	v_add_f32_dpp v112, v112, v112 quad_perm:[2,3,0,1] row_mask:0xf bank_mask:0xf
	s_nop 1
	v_add_f32_dpp v112, v112, v112 row_half_mirror row_mask:0xf bank_mask:0xf
	s_nop 1
	v_add_f32_dpp v112, v112, v112 row_mirror row_mask:0xf bank_mask:0xf
	s_nop 1
	v_readlane_b32 s98, v112, 0
	v_readlane_b32 s99, v112, 16
	v_readlane_b32 s100, v112, 32
	v_readlane_b32 vcc_lo, v112, 48
	s_nop 1
	v_mov_b32_e32 v113, s98
	v_add_f32_e32 v113, s99, v113
	v_add_f32_e32 v113, s100, v113
	v_add_f32_e32 v113, vcc_lo, v113
	v_fmamk_f32 v144, v113, 0x3b000000, v131
	v_rsq_f32_e32 v144, v144
	s_nop 0
	v_pk_mul_f32 v[146:147], v[146:147], v[144:145] op_sel_hi:[1,0]
	v_pk_mul_f32 v[148:149], v[148:149], v[144:145] op_sel_hi:[1,0]
	v_pk_mul_f32 v[150:151], v[150:151], v[144:145] op_sel_hi:[1,0]
	v_pk_mul_f32 v[152:153], v[152:153], v[144:145] op_sel_hi:[1,0]
	v_cvt_pk_bf16_f32 v116, v146, v147
	v_cvt_pk_bf16_f32 v117, v148, v149
	v_cvt_pk_bf16_f32 v118, v150, v151
	v_cvt_pk_bf16_f32 v119, v152, v153
	v_add_u32_e32 v138, 0xc00000, v135
	global_store_dwordx4 v138, v[116:119], s[34:35]
	v_add_u32_e32 v136, 0x1600000, v133
	v_add_u32_e32 v137, 0x4d00000, v134
	global_load_dwordx4 v[36:39], v136, s[22:23] nt
	global_load_dwordx4 v[40:43], v136, s[20:21] nt
	global_load_dwordx4 v[44:47], v137, s[38:39] nt
	s_waitcnt vmcnt(25)
	v_lshlrev_b32_e32 v146, 16, v48
	v_and_b32_e32 v147, 0xffff0000, v48
	v_lshlrev_b32_e32 v148, 16, v49
	v_and_b32_e32 v149, 0xffff0000, v49
	v_lshlrev_b32_e32 v150, 16, v50
	v_and_b32_e32 v151, 0xffff0000, v50
	v_lshlrev_b32_e32 v152, 16, v51
	v_and_b32_e32 v153, 0xffff0000, v51
	v_lshlrev_b32_e32 v154, 16, v52
	v_and_b32_e32 v155, 0xffff0000, v52
	v_lshlrev_b32_e32 v156, 16, v53
	v_and_b32_e32 v157, 0xffff0000, v53
	v_lshlrev_b32_e32 v158, 16, v54
	v_and_b32_e32 v159, 0xffff0000, v54
	v_lshlrev_b32_e32 v160, 16, v55
	v_and_b32_e32 v161, 0xffff0000, v55
	v_lshlrev_b32_e32 v162, 16, v56
	v_and_b32_e32 v163, 0xffff0000, v56
	v_lshlrev_b32_e32 v164, 16, v57
	v_and_b32_e32 v165, 0xffff0000, v57
	v_lshlrev_b32_e32 v166, 16, v58
	v_and_b32_e32 v167, 0xffff0000, v58
	v_lshlrev_b32_e32 v168, 16, v59
	v_and_b32_e32 v169, 0xffff0000, v59
	v_pk_add_f32 v[146:147], v[146:147], v[154:155]
	v_pk_add_f32 v[148:149], v[148:149], v[156:157]
	v_pk_add_f32 v[150:151], v[150:151], v[158:159]
	v_pk_add_f32 v[152:153], v[152:153], v[160:161]
	v_pk_mul_f32 v[170:171], v[162:163], v[162:163]
	v_pk_mul_f32 v[172:173], v[164:165], v[164:165]
	v_pk_mul_f32 v[174:175], v[166:167], v[166:167]
	v_pk_mul_f32 v[176:177], v[168:169], v[168:169]
	v_pk_fma_f32 v[170:171], v[170:171], v[140:141], v[142:143] op_sel_hi:[1,0,0]
	v_pk_fma_f32 v[172:173], v[172:173], v[140:141], v[142:143] op_sel_hi:[1,0,0]
	v_pk_fma_f32 v[174:175], v[174:175], v[140:141], v[142:143] op_sel_hi:[1,0,0]
	v_pk_fma_f32 v[176:177], v[176:177], v[140:141], v[142:143] op_sel_hi:[1,0,0]
	v_pk_mul_f32 v[170:171], v[170:171], v[162:163]
	v_pk_mul_f32 v[172:173], v[172:173], v[164:165]
	v_pk_mul_f32 v[174:175], v[174:175], v[166:167]
	v_pk_mul_f32 v[176:177], v[176:177], v[168:169]
	v_pk_mul_f32 v[154:155], v[146:147], v[162:163]
	v_pk_mul_f32 v[156:157], v[148:149], v[164:165]
	v_pk_mul_f32 v[158:159], v[150:151], v[166:167]
	v_pk_mul_f32 v[160:161], v[152:153], v[168:169]
	v_exp_f32_e32 v170, v170
	v_exp_f32_e32 v171, v171
	v_exp_f32_e32 v172, v172
	v_exp_f32_e32 v173, v173
	v_exp_f32_e32 v174, v174
	v_exp_f32_e32 v175, v175
	v_exp_f32_e32 v176, v176
	v_exp_f32_e32 v177, v177
	v_pk_add_f32 v[170:171], v[170:171], 1.0 op_sel_hi:[1,0]
	v_pk_add_f32 v[172:173], v[172:173], 1.0 op_sel_hi:[1,0]
	v_pk_add_f32 v[174:175], v[174:175], 1.0 op_sel_hi:[1,0]
	v_pk_add_f32 v[176:177], v[176:177], 1.0 op_sel_hi:[1,0]
	v_rcp_f32_e32 v170, v170
	v_rcp_f32_e32 v171, v171
	v_rcp_f32_e32 v172, v172
	v_rcp_f32_e32 v173, v173
	v_rcp_f32_e32 v174, v174
	v_rcp_f32_e32 v175, v175
	v_rcp_f32_e32 v176, v176
	v_rcp_f32_e32 v177, v177
	v_pk_mul_f32 v[96:97], v[154:155], v[170:171]
	v_pk_mul_f32 v[98:99], v[156:157], v[172:173]
	v_pk_mul_f32 v[100:101], v[158:159], v[174:175]
	v_pk_mul_f32 v[102:103], v[160:161], v[176:177]
	v_pk_mul_f32 v[112:113], v[96:97], v[96:97]
	v_pk_mul_f32 v[114:115], v[98:99], v[98:99]
	v_pk_fma_f32 v[112:113], v[100:101], v[100:101], v[112:113]
	v_pk_fma_f32 v[114:115], v[102:103], v[102:103], v[114:115]
	v_pk_add_f32 v[112:113], v[112:113], v[114:115]
	v_add_f32_e32 v112, v112, v113
	v_pk_mul_f32 v[146:147], v[96:97], v[120:121]
	v_pk_mul_f32 v[148:149], v[98:99], v[122:123]
	v_add_f32_dpp v112, v112, v112 quad_perm:[1,0,3,2] row_mask:0xf bank_mask:0xf
	v_pk_mul_f32 v[150:151], v[100:101], v[124:125]
	v_pk_mul_f32 v[152:153], v[102:103], v[126:127]
	v_add_f32_dpp v112, v112, v112 quad_perm:[2,3,0,1] row_mask:0xf bank_mask:0xf
	s_nop 1
	v_add_f32_dpp v112, v112, v112 row_half_mirror row_mask:0xf bank_mask:0xf
	s_nop 1
	v_add_f32_dpp v112, v112, v112 row_mirror row_mask:0xf bank_mask:0xf
	s_nop 1
	v_readlane_b32 s98, v112, 0
	v_readlane_b32 s99, v112, 16
	v_readlane_b32 s100, v112, 32
	v_readlane_b32 vcc_lo, v112, 48
	s_nop 1
	v_mov_b32_e32 v113, s98
	v_add_f32_e32 v113, s99, v113
	v_add_f32_e32 v113, s100, v113
	v_add_f32_e32 v113, vcc_lo, v113
	v_fmamk_f32 v144, v113, 0x3b000000, v131
	v_rsq_f32_e32 v144, v144
	s_nop 0
	v_pk_mul_f32 v[146:147], v[146:147], v[144:145] op_sel_hi:[1,0]
	v_pk_mul_f32 v[148:149], v[148:149], v[144:145] op_sel_hi:[1,0]
	v_pk_mul_f32 v[150:151], v[150:151], v[144:145] op_sel_hi:[1,0]
	v_pk_mul_f32 v[152:153], v[152:153], v[144:145] op_sel_hi:[1,0]
	v_cvt_pk_bf16_f32 v116, v146, v147
	v_cvt_pk_bf16_f32 v117, v148, v149
	v_cvt_pk_bf16_f32 v118, v150, v151
	v_cvt_pk_bf16_f32 v119, v152, v153
	v_add_u32_e32 v138, 0x1000000, v135
	global_store_dwordx4 v138, v[116:119], s[34:35]
	v_add_u32_e32 v136, 0x1800000, v133
	v_add_u32_e32 v137, 0x5400000, v134
	global_load_dwordx4 v[48:51], v136, s[22:23] nt
	global_load_dwordx4 v[52:55], v136, s[20:21] nt
	global_load_dwordx4 v[56:59], v137, s[38:39] nt
	s_waitcnt vmcnt(26)
	v_lshlrev_b32_e32 v146, 16, v60
	v_and_b32_e32 v147, 0xffff0000, v60
	v_lshlrev_b32_e32 v148, 16, v61
	v_and_b32_e32 v149, 0xffff0000, v61
	v_lshlrev_b32_e32 v150, 16, v62
	v_and_b32_e32 v151, 0xffff0000, v62
	v_lshlrev_b32_e32 v152, 16, v63
	v_and_b32_e32 v153, 0xffff0000, v63
	v_lshlrev_b32_e32 v154, 16, v64
	v_and_b32_e32 v155, 0xffff0000, v64
	v_lshlrev_b32_e32 v156, 16, v65
	v_and_b32_e32 v157, 0xffff0000, v65
	v_lshlrev_b32_e32 v158, 16, v66
	v_and_b32_e32 v159, 0xffff0000, v66
	v_lshlrev_b32_e32 v160, 16, v67
	v_and_b32_e32 v161, 0xffff0000, v67
	v_lshlrev_b32_e32 v162, 16, v68
	v_and_b32_e32 v163, 0xffff0000, v68
	v_lshlrev_b32_e32 v164, 16, v69
	v_and_b32_e32 v165, 0xffff0000, v69
	v_lshlrev_b32_e32 v166, 16, v70
	v_and_b32_e32 v167, 0xffff0000, v70
	v_lshlrev_b32_e32 v168, 16, v71
	v_and_b32_e32 v169, 0xffff0000, v71
	v_pk_add_f32 v[146:147], v[146:147], v[154:155]
	v_pk_add_f32 v[148:149], v[148:149], v[156:157]
	v_pk_add_f32 v[150:151], v[150:151], v[158:159]
	v_pk_add_f32 v[152:153], v[152:153], v[160:161]
	v_pk_mul_f32 v[170:171], v[162:163], v[162:163]
	v_pk_mul_f32 v[172:173], v[164:165], v[164:165]
	v_pk_mul_f32 v[174:175], v[166:167], v[166:167]
	v_pk_mul_f32 v[176:177], v[168:169], v[168:169]
	v_pk_fma_f32 v[170:171], v[170:171], v[140:141], v[142:143] op_sel_hi:[1,0,0]
	v_pk_fma_f32 v[172:173], v[172:173], v[140:141], v[142:143] op_sel_hi:[1,0,0]
	v_pk_fma_f32 v[174:175], v[174:175], v[140:141], v[142:143] op_sel_hi:[1,0,0]
	v_pk_fma_f32 v[176:177], v[176:177], v[140:141], v[142:143] op_sel_hi:[1,0,0]
	v_pk_mul_f32 v[170:171], v[170:171], v[162:163]
	v_pk_mul_f32 v[172:173], v[172:173], v[164:165]
	v_pk_mul_f32 v[174:175], v[174:175], v[166:167]
	v_pk_mul_f32 v[176:177], v[176:177], v[168:169]
	v_pk_mul_f32 v[154:155], v[146:147], v[162:163]
	v_pk_mul_f32 v[156:157], v[148:149], v[164:165]
	v_pk_mul_f32 v[158:159], v[150:151], v[166:167]
	v_pk_mul_f32 v[160:161], v[152:153], v[168:169]
	v_exp_f32_e32 v170, v170
	v_exp_f32_e32 v171, v171
	v_exp_f32_e32 v172, v172
	v_exp_f32_e32 v173, v173
	v_exp_f32_e32 v174, v174
	v_exp_f32_e32 v175, v175
	v_exp_f32_e32 v176, v176
	v_exp_f32_e32 v177, v177
	v_pk_add_f32 v[170:171], v[170:171], 1.0 op_sel_hi:[1,0]
	v_pk_add_f32 v[172:173], v[172:173], 1.0 op_sel_hi:[1,0]
	v_pk_add_f32 v[174:175], v[174:175], 1.0 op_sel_hi:[1,0]
	v_pk_add_f32 v[176:177], v[176:177], 1.0 op_sel_hi:[1,0]
	v_rcp_f32_e32 v170, v170
	v_rcp_f32_e32 v171, v171
	v_rcp_f32_e32 v172, v172
	v_rcp_f32_e32 v173, v173
	v_rcp_f32_e32 v174, v174
	v_rcp_f32_e32 v175, v175
	v_rcp_f32_e32 v176, v176
	v_rcp_f32_e32 v177, v177
	v_pk_mul_f32 v[96:97], v[154:155], v[170:171]
	v_pk_mul_f32 v[98:99], v[156:157], v[172:173]
	v_pk_mul_f32 v[100:101], v[158:159], v[174:175]
	v_pk_mul_f32 v[102:103], v[160:161], v[176:177]
	v_pk_mul_f32 v[112:113], v[96:97], v[96:97]
	v_pk_mul_f32 v[114:115], v[98:99], v[98:99]
	v_pk_fma_f32 v[112:113], v[100:101], v[100:101], v[112:113]
	v_pk_fma_f32 v[114:115], v[102:103], v[102:103], v[114:115]
	v_pk_add_f32 v[112:113], v[112:113], v[114:115]
	v_add_f32_e32 v112, v112, v113
	v_pk_mul_f32 v[146:147], v[96:97], v[120:121]
	v_pk_mul_f32 v[148:149], v[98:99], v[122:123]
	v_add_f32_dpp v112, v112, v112 quad_perm:[1,0,3,2] row_mask:0xf bank_mask:0xf
	v_pk_mul_f32 v[150:151], v[100:101], v[124:125]
	v_pk_mul_f32 v[152:153], v[102:103], v[126:127]
	v_add_f32_dpp v112, v112, v112 quad_perm:[2,3,0,1] row_mask:0xf bank_mask:0xf
	s_nop 1
	v_add_f32_dpp v112, v112, v112 row_half_mirror row_mask:0xf bank_mask:0xf
	s_nop 1
	v_add_f32_dpp v112, v112, v112 row_mirror row_mask:0xf bank_mask:0xf
	s_nop 1
	v_readlane_b32 s98, v112, 0
	v_readlane_b32 s99, v112, 16
	v_readlane_b32 s100, v112, 32
	v_readlane_b32 vcc_lo, v112, 48
	s_nop 1
	v_mov_b32_e32 v113, s98
	v_add_f32_e32 v113, s99, v113
	v_add_f32_e32 v113, s100, v113
	v_add_f32_e32 v113, vcc_lo, v113
	v_fmamk_f32 v144, v113, 0x3b000000, v131
	v_rsq_f32_e32 v144, v144
	s_nop 0
	v_pk_mul_f32 v[146:147], v[146:147], v[144:145] op_sel_hi:[1,0]
	v_pk_mul_f32 v[148:149], v[148:149], v[144:145] op_sel_hi:[1,0]
	v_pk_mul_f32 v[150:151], v[150:151], v[144:145] op_sel_hi:[1,0]
	v_pk_mul_f32 v[152:153], v[152:153], v[144:145] op_sel_hi:[1,0]
	v_cvt_pk_bf16_f32 v116, v146, v147
	v_cvt_pk_bf16_f32 v117, v148, v149
	v_cvt_pk_bf16_f32 v118, v150, v151
	v_cvt_pk_bf16_f32 v119, v152, v153
	v_add_u32_e32 v138, 0x1400000, v135
	global_store_dwordx4 v138, v[116:119], s[34:35]
	v_add_u32_e32 v136, 0x1a00000, v133
	v_add_u32_e32 v137, 0x5b00000, v134
	global_load_dwordx4 v[60:63], v136, s[22:23] nt
	global_load_dwordx4 v[64:67], v136, s[20:21] nt
	global_load_dwordx4 v[68:71], v137, s[38:39] nt
	s_waitcnt vmcnt(27)
	v_lshlrev_b32_e32 v146, 16, v72
	v_and_b32_e32 v147, 0xffff0000, v72
	v_lshlrev_b32_e32 v148, 16, v73
	v_and_b32_e32 v149, 0xffff0000, v73
	v_lshlrev_b32_e32 v150, 16, v74
	v_and_b32_e32 v151, 0xffff0000, v74
	v_lshlrev_b32_e32 v152, 16, v75
	v_and_b32_e32 v153, 0xffff0000, v75
	v_lshlrev_b32_e32 v154, 16, v76
	v_and_b32_e32 v155, 0xffff0000, v76
	v_lshlrev_b32_e32 v156, 16, v77
	v_and_b32_e32 v157, 0xffff0000, v77
	v_lshlrev_b32_e32 v158, 16, v78
	v_and_b32_e32 v159, 0xffff0000, v78
	v_lshlrev_b32_e32 v160, 16, v79
	v_and_b32_e32 v161, 0xffff0000, v79
	v_lshlrev_b32_e32 v162, 16, v80
	v_and_b32_e32 v163, 0xffff0000, v80
	v_lshlrev_b32_e32 v164, 16, v81
	v_and_b32_e32 v165, 0xffff0000, v81
	v_lshlrev_b32_e32 v166, 16, v82
	v_and_b32_e32 v167, 0xffff0000, v82
	v_lshlrev_b32_e32 v168, 16, v83
	v_and_b32_e32 v169, 0xffff0000, v83
	v_pk_add_f32 v[146:147], v[146:147], v[154:155]
	v_pk_add_f32 v[148:149], v[148:149], v[156:157]
	v_pk_add_f32 v[150:151], v[150:151], v[158:159]
	v_pk_add_f32 v[152:153], v[152:153], v[160:161]
	v_pk_mul_f32 v[170:171], v[162:163], v[162:163]
	v_pk_mul_f32 v[172:173], v[164:165], v[164:165]
	v_pk_mul_f32 v[174:175], v[166:167], v[166:167]
	v_pk_mul_f32 v[176:177], v[168:169], v[168:169]
	v_pk_fma_f32 v[170:171], v[170:171], v[140:141], v[142:143] op_sel_hi:[1,0,0]
	v_pk_fma_f32 v[172:173], v[172:173], v[140:141], v[142:143] op_sel_hi:[1,0,0]
	v_pk_fma_f32 v[174:175], v[174:175], v[140:141], v[142:143] op_sel_hi:[1,0,0]
	v_pk_fma_f32 v[176:177], v[176:177], v[140:141], v[142:143] op_sel_hi:[1,0,0]
	v_pk_mul_f32 v[170:171], v[170:171], v[162:163]
	v_pk_mul_f32 v[172:173], v[172:173], v[164:165]
	v_pk_mul_f32 v[174:175], v[174:175], v[166:167]
	v_pk_mul_f32 v[176:177], v[176:177], v[168:169]
	v_pk_mul_f32 v[154:155], v[146:147], v[162:163]
	v_pk_mul_f32 v[156:157], v[148:149], v[164:165]
	v_pk_mul_f32 v[158:159], v[150:151], v[166:167]
	v_pk_mul_f32 v[160:161], v[152:153], v[168:169]
	v_exp_f32_e32 v170, v170
	v_exp_f32_e32 v171, v171
	v_exp_f32_e32 v172, v172
	v_exp_f32_e32 v173, v173
	v_exp_f32_e32 v174, v174
	v_exp_f32_e32 v175, v175
	v_exp_f32_e32 v176, v176
	v_exp_f32_e32 v177, v177
	v_pk_add_f32 v[170:171], v[170:171], 1.0 op_sel_hi:[1,0]
	v_pk_add_f32 v[172:173], v[172:173], 1.0 op_sel_hi:[1,0]
	v_pk_add_f32 v[174:175], v[174:175], 1.0 op_sel_hi:[1,0]
	v_pk_add_f32 v[176:177], v[176:177], 1.0 op_sel_hi:[1,0]
	v_rcp_f32_e32 v170, v170
	v_rcp_f32_e32 v171, v171
	v_rcp_f32_e32 v172, v172
	v_rcp_f32_e32 v173, v173
	v_rcp_f32_e32 v174, v174
	v_rcp_f32_e32 v175, v175
	v_rcp_f32_e32 v176, v176
	v_rcp_f32_e32 v177, v177
	v_pk_mul_f32 v[96:97], v[154:155], v[170:171]
	v_pk_mul_f32 v[98:99], v[156:157], v[172:173]
	v_pk_mul_f32 v[100:101], v[158:159], v[174:175]
	v_pk_mul_f32 v[102:103], v[160:161], v[176:177]
	v_pk_mul_f32 v[112:113], v[96:97], v[96:97]
	v_pk_mul_f32 v[114:115], v[98:99], v[98:99]
	v_pk_fma_f32 v[112:113], v[100:101], v[100:101], v[112:113]
	v_pk_fma_f32 v[114:115], v[102:103], v[102:103], v[114:115]
	v_pk_add_f32 v[112:113], v[112:113], v[114:115]
	v_add_f32_e32 v112, v112, v113
	v_pk_mul_f32 v[146:147], v[96:97], v[120:121]
	v_pk_mul_f32 v[148:149], v[98:99], v[122:123]
	v_add_f32_dpp v112, v112, v112 quad_perm:[1,0,3,2] row_mask:0xf bank_mask:0xf
	v_pk_mul_f32 v[150:151], v[100:101], v[124:125]
	v_pk_mul_f32 v[152:153], v[102:103], v[126:127]
	v_add_f32_dpp v112, v112, v112 quad_perm:[2,3,0,1] row_mask:0xf bank_mask:0xf
	s_nop 1
	v_add_f32_dpp v112, v112, v112 row_half_mirror row_mask:0xf bank_mask:0xf
	s_nop 1
	v_add_f32_dpp v112, v112, v112 row_mirror row_mask:0xf bank_mask:0xf
	s_nop 1
	v_readlane_b32 s98, v112, 0
	v_readlane_b32 s99, v112, 16
	v_readlane_b32 s100, v112, 32
	v_readlane_b32 vcc_lo, v112, 48
	s_nop 1
	v_mov_b32_e32 v113, s98
	v_add_f32_e32 v113, s99, v113
	v_add_f32_e32 v113, s100, v113
	v_add_f32_e32 v113, vcc_lo, v113
	v_fmamk_f32 v144, v113, 0x3b000000, v131
	v_rsq_f32_e32 v144, v144
	s_nop 0
	v_pk_mul_f32 v[146:147], v[146:147], v[144:145] op_sel_hi:[1,0]
	v_pk_mul_f32 v[148:149], v[148:149], v[144:145] op_sel_hi:[1,0]
	v_pk_mul_f32 v[150:151], v[150:151], v[144:145] op_sel_hi:[1,0]
	v_pk_mul_f32 v[152:153], v[152:153], v[144:145] op_sel_hi:[1,0]
	v_cvt_pk_bf16_f32 v116, v146, v147
	v_cvt_pk_bf16_f32 v117, v148, v149
	v_cvt_pk_bf16_f32 v118, v150, v151
	v_cvt_pk_bf16_f32 v119, v152, v153
	v_add_u32_e32 v138, 0x1800000, v135
	global_store_dwordx4 v138, v[116:119], s[34:35]
	v_add_u32_e32 v136, 0x1c00000, v133
	v_add_u32_e32 v137, 0x6200000, v134
	global_load_dwordx4 v[72:75], v136, s[22:23] nt
	global_load_dwordx4 v[76:79], v136, s[20:21] nt
	global_load_dwordx4 v[80:83], v137, s[38:39] nt
	s_waitcnt vmcnt(28)
	v_lshlrev_b32_e32 v146, 16, v84
	v_and_b32_e32 v147, 0xffff0000, v84
	v_lshlrev_b32_e32 v148, 16, v85
	v_and_b32_e32 v149, 0xffff0000, v85
	v_lshlrev_b32_e32 v150, 16, v86
	v_and_b32_e32 v151, 0xffff0000, v86
	v_lshlrev_b32_e32 v152, 16, v87
	v_and_b32_e32 v153, 0xffff0000, v87
	v_lshlrev_b32_e32 v154, 16, v88
	v_and_b32_e32 v155, 0xffff0000, v88
	v_lshlrev_b32_e32 v156, 16, v89
	v_and_b32_e32 v157, 0xffff0000, v89
	v_lshlrev_b32_e32 v158, 16, v90
	v_and_b32_e32 v159, 0xffff0000, v90
	v_lshlrev_b32_e32 v160, 16, v91
	v_and_b32_e32 v161, 0xffff0000, v91
	v_lshlrev_b32_e32 v162, 16, v92
	v_and_b32_e32 v163, 0xffff0000, v92
	v_lshlrev_b32_e32 v164, 16, v93
	v_and_b32_e32 v165, 0xffff0000, v93
	v_lshlrev_b32_e32 v166, 16, v94
	v_and_b32_e32 v167, 0xffff0000, v94
	v_lshlrev_b32_e32 v168, 16, v95
	v_and_b32_e32 v169, 0xffff0000, v95
	v_pk_add_f32 v[146:147], v[146:147], v[154:155]
	v_pk_add_f32 v[148:149], v[148:149], v[156:157]
	v_pk_add_f32 v[150:151], v[150:151], v[158:159]
	v_pk_add_f32 v[152:153], v[152:153], v[160:161]
	v_pk_mul_f32 v[170:171], v[162:163], v[162:163]
	v_pk_mul_f32 v[172:173], v[164:165], v[164:165]
	v_pk_mul_f32 v[174:175], v[166:167], v[166:167]
	v_pk_mul_f32 v[176:177], v[168:169], v[168:169]
	v_pk_fma_f32 v[170:171], v[170:171], v[140:141], v[142:143] op_sel_hi:[1,0,0]
	v_pk_fma_f32 v[172:173], v[172:173], v[140:141], v[142:143] op_sel_hi:[1,0,0]
	v_pk_fma_f32 v[174:175], v[174:175], v[140:141], v[142:143] op_sel_hi:[1,0,0]
	v_pk_fma_f32 v[176:177], v[176:177], v[140:141], v[142:143] op_sel_hi:[1,0,0]
	v_pk_mul_f32 v[170:171], v[170:171], v[162:163]
	v_pk_mul_f32 v[172:173], v[172:173], v[164:165]
	v_pk_mul_f32 v[174:175], v[174:175], v[166:167]
	v_pk_mul_f32 v[176:177], v[176:177], v[168:169]
	v_pk_mul_f32 v[154:155], v[146:147], v[162:163]
	v_pk_mul_f32 v[156:157], v[148:149], v[164:165]
	v_pk_mul_f32 v[158:159], v[150:151], v[166:167]
	v_pk_mul_f32 v[160:161], v[152:153], v[168:169]
	v_exp_f32_e32 v170, v170
	v_exp_f32_e32 v171, v171
	v_exp_f32_e32 v172, v172
	v_exp_f32_e32 v173, v173
	v_exp_f32_e32 v174, v174
	v_exp_f32_e32 v175, v175
	v_exp_f32_e32 v176, v176
	v_exp_f32_e32 v177, v177
	v_pk_add_f32 v[170:171], v[170:171], 1.0 op_sel_hi:[1,0]
	v_pk_add_f32 v[172:173], v[172:173], 1.0 op_sel_hi:[1,0]
	v_pk_add_f32 v[174:175], v[174:175], 1.0 op_sel_hi:[1,0]
	v_pk_add_f32 v[176:177], v[176:177], 1.0 op_sel_hi:[1,0]
	v_rcp_f32_e32 v170, v170
	v_rcp_f32_e32 v171, v171
	v_rcp_f32_e32 v172, v172
	v_rcp_f32_e32 v173, v173
	v_rcp_f32_e32 v174, v174
	v_rcp_f32_e32 v175, v175
	v_rcp_f32_e32 v176, v176
	v_rcp_f32_e32 v177, v177
	v_pk_mul_f32 v[96:97], v[154:155], v[170:171]
	v_pk_mul_f32 v[98:99], v[156:157], v[172:173]
	v_pk_mul_f32 v[100:101], v[158:159], v[174:175]
	v_pk_mul_f32 v[102:103], v[160:161], v[176:177]
	v_pk_mul_f32 v[112:113], v[96:97], v[96:97]
	v_pk_mul_f32 v[114:115], v[98:99], v[98:99]
	v_pk_fma_f32 v[112:113], v[100:101], v[100:101], v[112:113]
	v_pk_fma_f32 v[114:115], v[102:103], v[102:103], v[114:115]
	v_pk_add_f32 v[112:113], v[112:113], v[114:115]
	v_add_f32_e32 v112, v112, v113
	v_pk_mul_f32 v[146:147], v[96:97], v[120:121]
	v_pk_mul_f32 v[148:149], v[98:99], v[122:123]
	v_add_f32_dpp v112, v112, v112 quad_perm:[1,0,3,2] row_mask:0xf bank_mask:0xf
	v_pk_mul_f32 v[150:151], v[100:101], v[124:125]
	v_pk_mul_f32 v[152:153], v[102:103], v[126:127]
	v_add_f32_dpp v112, v112, v112 quad_perm:[2,3,0,1] row_mask:0xf bank_mask:0xf
	s_nop 1
	v_add_f32_dpp v112, v112, v112 row_half_mirror row_mask:0xf bank_mask:0xf
	s_nop 1
	v_add_f32_dpp v112, v112, v112 row_mirror row_mask:0xf bank_mask:0xf
	s_nop 1
	v_readlane_b32 s98, v112, 0
	v_readlane_b32 s99, v112, 16
	v_readlane_b32 s100, v112, 32
	v_readlane_b32 vcc_lo, v112, 48
	s_nop 1
	v_mov_b32_e32 v113, s98
	v_add_f32_e32 v113, s99, v113
	v_add_f32_e32 v113, s100, v113
	v_add_f32_e32 v113, vcc_lo, v113
	v_fmamk_f32 v144, v113, 0x3b000000, v131
	v_rsq_f32_e32 v144, v144
	s_nop 0
	v_pk_mul_f32 v[146:147], v[146:147], v[144:145] op_sel_hi:[1,0]
	v_pk_mul_f32 v[148:149], v[148:149], v[144:145] op_sel_hi:[1,0]
	v_pk_mul_f32 v[150:151], v[150:151], v[144:145] op_sel_hi:[1,0]
	v_pk_mul_f32 v[152:153], v[152:153], v[144:145] op_sel_hi:[1,0]
	v_cvt_pk_bf16_f32 v116, v146, v147
	v_cvt_pk_bf16_f32 v117, v148, v149
	v_cvt_pk_bf16_f32 v118, v150, v151
	v_cvt_pk_bf16_f32 v119, v152, v153
	v_add_u32_e32 v138, 0x1c00000, v135
	global_store_dwordx4 v138, v[116:119], s[34:35]
	v_add_u32_e32 v136, 0x1e00000, v133
	v_add_u32_e32 v137, 0x6900000, v134
	global_load_dwordx4 v[84:87], v136, s[22:23] nt
	global_load_dwordx4 v[88:91], v136, s[20:21] nt
	global_load_dwordx4 v[92:95], v137, s[38:39] nt
	s_waitcnt vmcnt(28)
	v_lshlrev_b32_e32 v146, 16, v0
	v_and_b32_e32 v147, 0xffff0000, v0
	v_lshlrev_b32_e32 v148, 16, v1
	v_and_b32_e32 v149, 0xffff0000, v1
	v_lshlrev_b32_e32 v150, 16, v2
	v_and_b32_e32 v151, 0xffff0000, v2
	v_lshlrev_b32_e32 v152, 16, v3
	v_and_b32_e32 v153, 0xffff0000, v3
	v_lshlrev_b32_e32 v154, 16, v4
	v_and_b32_e32 v155, 0xffff0000, v4
	v_lshlrev_b32_e32 v156, 16, v5
	v_and_b32_e32 v157, 0xffff0000, v5
	v_lshlrev_b32_e32 v158, 16, v6
	v_and_b32_e32 v159, 0xffff0000, v6
	v_lshlrev_b32_e32 v160, 16, v7
	v_and_b32_e32 v161, 0xffff0000, v7
	v_lshlrev_b32_e32 v162, 16, v8
	v_and_b32_e32 v163, 0xffff0000, v8
	v_lshlrev_b32_e32 v164, 16, v9
	v_and_b32_e32 v165, 0xffff0000, v9
	v_lshlrev_b32_e32 v166, 16, v10
	v_and_b32_e32 v167, 0xffff0000, v10
	v_lshlrev_b32_e32 v168, 16, v11
	v_and_b32_e32 v169, 0xffff0000, v11
	v_pk_add_f32 v[146:147], v[146:147], v[154:155]
	v_pk_add_f32 v[148:149], v[148:149], v[156:157]
	v_pk_add_f32 v[150:151], v[150:151], v[158:159]
	v_pk_add_f32 v[152:153], v[152:153], v[160:161]
	v_pk_mul_f32 v[170:171], v[162:163], v[162:163]
	v_pk_mul_f32 v[172:173], v[164:165], v[164:165]
	v_pk_mul_f32 v[174:175], v[166:167], v[166:167]
	v_pk_mul_f32 v[176:177], v[168:169], v[168:169]
	v_pk_fma_f32 v[170:171], v[170:171], v[140:141], v[142:143] op_sel_hi:[1,0,0]
	v_pk_fma_f32 v[172:173], v[172:173], v[140:141], v[142:143] op_sel_hi:[1,0,0]
	v_pk_fma_f32 v[174:175], v[174:175], v[140:141], v[142:143] op_sel_hi:[1,0,0]
	v_pk_fma_f32 v[176:177], v[176:177], v[140:141], v[142:143] op_sel_hi:[1,0,0]
	v_pk_mul_f32 v[170:171], v[170:171], v[162:163]
	v_pk_mul_f32 v[172:173], v[172:173], v[164:165]
	v_pk_mul_f32 v[174:175], v[174:175], v[166:167]
	v_pk_mul_f32 v[176:177], v[176:177], v[168:169]
	v_pk_mul_f32 v[154:155], v[146:147], v[162:163]
	v_pk_mul_f32 v[156:157], v[148:149], v[164:165]
	v_pk_mul_f32 v[158:159], v[150:151], v[166:167]
	v_pk_mul_f32 v[160:161], v[152:153], v[168:169]
	v_exp_f32_e32 v170, v170
	v_exp_f32_e32 v171, v171
	v_exp_f32_e32 v172, v172
	v_exp_f32_e32 v173, v173
	v_exp_f32_e32 v174, v174
	v_exp_f32_e32 v175, v175
	v_exp_f32_e32 v176, v176
	v_exp_f32_e32 v177, v177
	v_pk_add_f32 v[170:171], v[170:171], 1.0 op_sel_hi:[1,0]
	v_pk_add_f32 v[172:173], v[172:173], 1.0 op_sel_hi:[1,0]
	v_pk_add_f32 v[174:175], v[174:175], 1.0 op_sel_hi:[1,0]
	v_pk_add_f32 v[176:177], v[176:177], 1.0 op_sel_hi:[1,0]
	v_rcp_f32_e32 v170, v170
	v_rcp_f32_e32 v171, v171
	v_rcp_f32_e32 v172, v172
	v_rcp_f32_e32 v173, v173
	v_rcp_f32_e32 v174, v174
	v_rcp_f32_e32 v175, v175
	v_rcp_f32_e32 v176, v176
	v_rcp_f32_e32 v177, v177
	v_pk_mul_f32 v[96:97], v[154:155], v[170:171]
	v_pk_mul_f32 v[98:99], v[156:157], v[172:173]
	v_pk_mul_f32 v[100:101], v[158:159], v[174:175]
	v_pk_mul_f32 v[102:103], v[160:161], v[176:177]
	v_pk_mul_f32 v[112:113], v[96:97], v[96:97]
	v_pk_mul_f32 v[114:115], v[98:99], v[98:99]
	v_pk_fma_f32 v[112:113], v[100:101], v[100:101], v[112:113]
	v_pk_fma_f32 v[114:115], v[102:103], v[102:103], v[114:115]
	v_pk_add_f32 v[112:113], v[112:113], v[114:115]
	v_add_f32_e32 v112, v112, v113
	v_pk_mul_f32 v[146:147], v[96:97], v[120:121]
	v_pk_mul_f32 v[148:149], v[98:99], v[122:123]
	v_add_f32_dpp v112, v112, v112 quad_perm:[1,0,3,2] row_mask:0xf bank_mask:0xf
	v_pk_mul_f32 v[150:151], v[100:101], v[124:125]
	v_pk_mul_f32 v[152:153], v[102:103], v[126:127]
	v_add_f32_dpp v112, v112, v112 quad_perm:[2,3,0,1] row_mask:0xf bank_mask:0xf
	s_nop 1
	v_add_f32_dpp v112, v112, v112 row_half_mirror row_mask:0xf bank_mask:0xf
	s_nop 1
	v_add_f32_dpp v112, v112, v112 row_mirror row_mask:0xf bank_mask:0xf
	s_nop 1
	v_readlane_b32 s98, v112, 0
	v_readlane_b32 s99, v112, 16
	v_readlane_b32 s100, v112, 32
	v_readlane_b32 vcc_lo, v112, 48
	s_nop 1
	v_mov_b32_e32 v113, s98
	v_add_f32_e32 v113, s99, v113
	v_add_f32_e32 v113, s100, v113
	v_add_f32_e32 v113, vcc_lo, v113
	v_fmamk_f32 v144, v113, 0x3b000000, v131
	v_rsq_f32_e32 v144, v144
	s_nop 0
	v_pk_mul_f32 v[146:147], v[146:147], v[144:145] op_sel_hi:[1,0]
	v_pk_mul_f32 v[148:149], v[148:149], v[144:145] op_sel_hi:[1,0]
	v_pk_mul_f32 v[150:151], v[150:151], v[144:145] op_sel_hi:[1,0]
	v_pk_mul_f32 v[152:153], v[152:153], v[144:145] op_sel_hi:[1,0]
	v_cvt_pk_bf16_f32 v116, v146, v147
	v_cvt_pk_bf16_f32 v117, v148, v149
	v_cvt_pk_bf16_f32 v118, v150, v151
	v_cvt_pk_bf16_f32 v119, v152, v153
	v_add_u32_e32 v138, 0x2000000, v135
	global_store_dwordx4 v138, v[116:119], s[34:35]
	s_waitcnt vmcnt(25)
	v_lshlrev_b32_e32 v146, 16, v12
	v_and_b32_e32 v147, 0xffff0000, v12
	v_lshlrev_b32_e32 v148, 16, v13
	v_and_b32_e32 v149, 0xffff0000, v13
	v_lshlrev_b32_e32 v150, 16, v14
	v_and_b32_e32 v151, 0xffff0000, v14
	v_lshlrev_b32_e32 v152, 16, v15
	v_and_b32_e32 v153, 0xffff0000, v15
	v_lshlrev_b32_e32 v154, 16, v16
	v_and_b32_e32 v155, 0xffff0000, v16
	v_lshlrev_b32_e32 v156, 16, v17
	v_and_b32_e32 v157, 0xffff0000, v17
	v_lshlrev_b32_e32 v158, 16, v18
	v_and_b32_e32 v159, 0xffff0000, v18
	v_lshlrev_b32_e32 v160, 16, v19
	v_and_b32_e32 v161, 0xffff0000, v19
	v_lshlrev_b32_e32 v162, 16, v20
	v_and_b32_e32 v163, 0xffff0000, v20
	v_lshlrev_b32_e32 v164, 16, v21
	v_and_b32_e32 v165, 0xffff0000, v21
	v_lshlrev_b32_e32 v166, 16, v22
	v_and_b32_e32 v167, 0xffff0000, v22
	v_lshlrev_b32_e32 v168, 16, v23
	v_and_b32_e32 v169, 0xffff0000, v23
	v_pk_add_f32 v[146:147], v[146:147], v[154:155]
	v_pk_add_f32 v[148:149], v[148:149], v[156:157]
	v_pk_add_f32 v[150:151], v[150:151], v[158:159]
	v_pk_add_f32 v[152:153], v[152:153], v[160:161]
	v_pk_mul_f32 v[170:171], v[162:163], v[162:163]
	v_pk_mul_f32 v[172:173], v[164:165], v[164:165]
	v_pk_mul_f32 v[174:175], v[166:167], v[166:167]
	v_pk_mul_f32 v[176:177], v[168:169], v[168:169]
	v_pk_fma_f32 v[170:171], v[170:171], v[140:141], v[142:143] op_sel_hi:[1,0,0]
	v_pk_fma_f32 v[172:173], v[172:173], v[140:141], v[142:143] op_sel_hi:[1,0,0]
	v_pk_fma_f32 v[174:175], v[174:175], v[140:141], v[142:143] op_sel_hi:[1,0,0]
	v_pk_fma_f32 v[176:177], v[176:177], v[140:141], v[142:143] op_sel_hi:[1,0,0]
	v_pk_mul_f32 v[170:171], v[170:171], v[162:163]
	v_pk_mul_f32 v[172:173], v[172:173], v[164:165]
	v_pk_mul_f32 v[174:175], v[174:175], v[166:167]
	v_pk_mul_f32 v[176:177], v[176:177], v[168:169]
	v_pk_mul_f32 v[154:155], v[146:147], v[162:163]
	v_pk_mul_f32 v[156:157], v[148:149], v[164:165]
	v_pk_mul_f32 v[158:159], v[150:151], v[166:167]
	v_pk_mul_f32 v[160:161], v[152:153], v[168:169]
	v_exp_f32_e32 v170, v170
	v_exp_f32_e32 v171, v171
	v_exp_f32_e32 v172, v172
	v_exp_f32_e32 v173, v173
	v_exp_f32_e32 v174, v174
	v_exp_f32_e32 v175, v175
	v_exp_f32_e32 v176, v176
	v_exp_f32_e32 v177, v177
	v_pk_add_f32 v[170:171], v[170:171], 1.0 op_sel_hi:[1,0]
	v_pk_add_f32 v[172:173], v[172:173], 1.0 op_sel_hi:[1,0]
	v_pk_add_f32 v[174:175], v[174:175], 1.0 op_sel_hi:[1,0]
	v_pk_add_f32 v[176:177], v[176:177], 1.0 op_sel_hi:[1,0]
	v_rcp_f32_e32 v170, v170
	v_rcp_f32_e32 v171, v171
	v_rcp_f32_e32 v172, v172
	v_rcp_f32_e32 v173, v173
	v_rcp_f32_e32 v174, v174
	v_rcp_f32_e32 v175, v175
	v_rcp_f32_e32 v176, v176
	v_rcp_f32_e32 v177, v177
	v_pk_mul_f32 v[96:97], v[154:155], v[170:171]
	v_pk_mul_f32 v[98:99], v[156:157], v[172:173]
	v_pk_mul_f32 v[100:101], v[158:159], v[174:175]
	v_pk_mul_f32 v[102:103], v[160:161], v[176:177]
	v_pk_mul_f32 v[112:113], v[96:97], v[96:97]
	v_pk_mul_f32 v[114:115], v[98:99], v[98:99]
	v_pk_fma_f32 v[112:113], v[100:101], v[100:101], v[112:113]
	v_pk_fma_f32 v[114:115], v[102:103], v[102:103], v[114:115]
	v_pk_add_f32 v[112:113], v[112:113], v[114:115]
	v_add_f32_e32 v112, v112, v113
	v_pk_mul_f32 v[146:147], v[96:97], v[120:121]
	v_pk_mul_f32 v[148:149], v[98:99], v[122:123]
	v_add_f32_dpp v112, v112, v112 quad_perm:[1,0,3,2] row_mask:0xf bank_mask:0xf
	v_pk_mul_f32 v[150:151], v[100:101], v[124:125]
	v_pk_mul_f32 v[152:153], v[102:103], v[126:127]
	v_add_f32_dpp v112, v112, v112 quad_perm:[2,3,0,1] row_mask:0xf bank_mask:0xf
	s_nop 1
	v_add_f32_dpp v112, v112, v112 row_half_mirror row_mask:0xf bank_mask:0xf
	s_nop 1
	v_add_f32_dpp v112, v112, v112 row_mirror row_mask:0xf bank_mask:0xf
	s_nop 1
	v_readlane_b32 s98, v112, 0
	v_readlane_b32 s99, v112, 16
	v_readlane_b32 s100, v112, 32
	v_readlane_b32 vcc_lo, v112, 48
	s_nop 1
	v_mov_b32_e32 v113, s98
	v_add_f32_e32 v113, s99, v113
	v_add_f32_e32 v113, s100, v113
	v_add_f32_e32 v113, vcc_lo, v113
	v_fmamk_f32 v144, v113, 0x3b000000, v131
	v_rsq_f32_e32 v144, v144
	s_nop 0
	v_pk_mul_f32 v[146:147], v[146:147], v[144:145] op_sel_hi:[1,0]
	v_pk_mul_f32 v[148:149], v[148:149], v[144:145] op_sel_hi:[1,0]
	v_pk_mul_f32 v[150:151], v[150:151], v[144:145] op_sel_hi:[1,0]
	v_pk_mul_f32 v[152:153], v[152:153], v[144:145] op_sel_hi:[1,0]
	v_cvt_pk_bf16_f32 v116, v146, v147
	v_cvt_pk_bf16_f32 v117, v148, v149
	v_cvt_pk_bf16_f32 v118, v150, v151
	v_cvt_pk_bf16_f32 v119, v152, v153
	v_add_u32_e32 v138, 0x2400000, v135
	global_store_dwordx4 v138, v[116:119], s[34:35]
	s_waitcnt vmcnt(22)
	v_lshlrev_b32_e32 v146, 16, v24
	v_and_b32_e32 v147, 0xffff0000, v24
	v_lshlrev_b32_e32 v148, 16, v25
	v_and_b32_e32 v149, 0xffff0000, v25
	v_lshlrev_b32_e32 v150, 16, v26
	v_and_b32_e32 v151, 0xffff0000, v26
	v_lshlrev_b32_e32 v152, 16, v27
	v_and_b32_e32 v153, 0xffff0000, v27
	v_lshlrev_b32_e32 v154, 16, v28
	v_and_b32_e32 v155, 0xffff0000, v28
	v_lshlrev_b32_e32 v156, 16, v29
	v_and_b32_e32 v157, 0xffff0000, v29
	v_lshlrev_b32_e32 v158, 16, v30
	v_and_b32_e32 v159, 0xffff0000, v30
	v_lshlrev_b32_e32 v160, 16, v31
	v_and_b32_e32 v161, 0xffff0000, v31
	v_lshlrev_b32_e32 v162, 16, v32
	v_and_b32_e32 v163, 0xffff0000, v32
	v_lshlrev_b32_e32 v164, 16, v33
	v_and_b32_e32 v165, 0xffff0000, v33
	v_lshlrev_b32_e32 v166, 16, v34
	v_and_b32_e32 v167, 0xffff0000, v34
	v_lshlrev_b32_e32 v168, 16, v35
	v_and_b32_e32 v169, 0xffff0000, v35
	v_pk_add_f32 v[146:147], v[146:147], v[154:155]
	v_pk_add_f32 v[148:149], v[148:149], v[156:157]
	v_pk_add_f32 v[150:151], v[150:151], v[158:159]
	v_pk_add_f32 v[152:153], v[152:153], v[160:161]
	v_pk_mul_f32 v[170:171], v[162:163], v[162:163]
	v_pk_mul_f32 v[172:173], v[164:165], v[164:165]
	v_pk_mul_f32 v[174:175], v[166:167], v[166:167]
	v_pk_mul_f32 v[176:177], v[168:169], v[168:169]
	v_pk_fma_f32 v[170:171], v[170:171], v[140:141], v[142:143] op_sel_hi:[1,0,0]
	v_pk_fma_f32 v[172:173], v[172:173], v[140:141], v[142:143] op_sel_hi:[1,0,0]
	v_pk_fma_f32 v[174:175], v[174:175], v[140:141], v[142:143] op_sel_hi:[1,0,0]
	v_pk_fma_f32 v[176:177], v[176:177], v[140:141], v[142:143] op_sel_hi:[1,0,0]
	v_pk_mul_f32 v[170:171], v[170:171], v[162:163]
	v_pk_mul_f32 v[172:173], v[172:173], v[164:165]
	v_pk_mul_f32 v[174:175], v[174:175], v[166:167]
	v_pk_mul_f32 v[176:177], v[176:177], v[168:169]
	v_pk_mul_f32 v[154:155], v[146:147], v[162:163]
	v_pk_mul_f32 v[156:157], v[148:149], v[164:165]
	v_pk_mul_f32 v[158:159], v[150:151], v[166:167]
	v_pk_mul_f32 v[160:161], v[152:153], v[168:169]
	v_exp_f32_e32 v170, v170
	v_exp_f32_e32 v171, v171
	v_exp_f32_e32 v172, v172
	v_exp_f32_e32 v173, v173
	v_exp_f32_e32 v174, v174
	v_exp_f32_e32 v175, v175
	v_exp_f32_e32 v176, v176
	v_exp_f32_e32 v177, v177
	v_pk_add_f32 v[170:171], v[170:171], 1.0 op_sel_hi:[1,0]
	v_pk_add_f32 v[172:173], v[172:173], 1.0 op_sel_hi:[1,0]
	v_pk_add_f32 v[174:175], v[174:175], 1.0 op_sel_hi:[1,0]
	v_pk_add_f32 v[176:177], v[176:177], 1.0 op_sel_hi:[1,0]
	v_rcp_f32_e32 v170, v170
	v_rcp_f32_e32 v171, v171
	v_rcp_f32_e32 v172, v172
	v_rcp_f32_e32 v173, v173
	v_rcp_f32_e32 v174, v174
	v_rcp_f32_e32 v175, v175
	v_rcp_f32_e32 v176, v176
	v_rcp_f32_e32 v177, v177
	v_pk_mul_f32 v[96:97], v[154:155], v[170:171]
	v_pk_mul_f32 v[98:99], v[156:157], v[172:173]
	v_pk_mul_f32 v[100:101], v[158:159], v[174:175]
	v_pk_mul_f32 v[102:103], v[160:161], v[176:177]
	v_pk_mul_f32 v[112:113], v[96:97], v[96:97]
	v_pk_mul_f32 v[114:115], v[98:99], v[98:99]
	v_pk_fma_f32 v[112:113], v[100:101], v[100:101], v[112:113]
	v_pk_fma_f32 v[114:115], v[102:103], v[102:103], v[114:115]
	v_pk_add_f32 v[112:113], v[112:113], v[114:115]
	v_add_f32_e32 v112, v112, v113
	v_pk_mul_f32 v[146:147], v[96:97], v[120:121]
	v_pk_mul_f32 v[148:149], v[98:99], v[122:123]
	v_add_f32_dpp v112, v112, v112 quad_perm:[1,0,3,2] row_mask:0xf bank_mask:0xf
	v_pk_mul_f32 v[150:151], v[100:101], v[124:125]
	v_pk_mul_f32 v[152:153], v[102:103], v[126:127]
	v_add_f32_dpp v112, v112, v112 quad_perm:[2,3,0,1] row_mask:0xf bank_mask:0xf
	s_nop 1
	v_add_f32_dpp v112, v112, v112 row_half_mirror row_mask:0xf bank_mask:0xf
	s_nop 1
	v_add_f32_dpp v112, v112, v112 row_mirror row_mask:0xf bank_mask:0xf
	s_nop 1
	v_readlane_b32 s98, v112, 0
	v_readlane_b32 s99, v112, 16
	v_readlane_b32 s100, v112, 32
	v_readlane_b32 vcc_lo, v112, 48
	s_nop 1
	v_mov_b32_e32 v113, s98
	v_add_f32_e32 v113, s99, v113
	v_add_f32_e32 v113, s100, v113
	v_add_f32_e32 v113, vcc_lo, v113
	v_fmamk_f32 v144, v113, 0x3b000000, v131
	v_rsq_f32_e32 v144, v144
	s_nop 0
	v_pk_mul_f32 v[146:147], v[146:147], v[144:145] op_sel_hi:[1,0]
	v_pk_mul_f32 v[148:149], v[148:149], v[144:145] op_sel_hi:[1,0]
	v_pk_mul_f32 v[150:151], v[150:151], v[144:145] op_sel_hi:[1,0]
	v_pk_mul_f32 v[152:153], v[152:153], v[144:145] op_sel_hi:[1,0]
	v_cvt_pk_bf16_f32 v116, v146, v147
	v_cvt_pk_bf16_f32 v117, v148, v149
	v_cvt_pk_bf16_f32 v118, v150, v151
	v_cvt_pk_bf16_f32 v119, v152, v153
	v_add_u32_e32 v138, 0x2800000, v135
	global_store_dwordx4 v138, v[116:119], s[34:35]
	s_waitcnt vmcnt(19)
	v_lshlrev_b32_e32 v146, 16, v36
	v_and_b32_e32 v147, 0xffff0000, v36
	v_lshlrev_b32_e32 v148, 16, v37
	v_and_b32_e32 v149, 0xffff0000, v37
	v_lshlrev_b32_e32 v150, 16, v38
	v_and_b32_e32 v151, 0xffff0000, v38
	v_lshlrev_b32_e32 v152, 16, v39
	v_and_b32_e32 v153, 0xffff0000, v39
	v_lshlrev_b32_e32 v154, 16, v40
	v_and_b32_e32 v155, 0xffff0000, v40
	v_lshlrev_b32_e32 v156, 16, v41
	v_and_b32_e32 v157, 0xffff0000, v41
	v_lshlrev_b32_e32 v158, 16, v42
	v_and_b32_e32 v159, 0xffff0000, v42
	v_lshlrev_b32_e32 v160, 16, v43
	v_and_b32_e32 v161, 0xffff0000, v43
	v_lshlrev_b32_e32 v162, 16, v44
	v_and_b32_e32 v163, 0xffff0000, v44
	v_lshlrev_b32_e32 v164, 16, v45
	v_and_b32_e32 v165, 0xffff0000, v45
	v_lshlrev_b32_e32 v166, 16, v46
	v_and_b32_e32 v167, 0xffff0000, v46
	v_lshlrev_b32_e32 v168, 16, v47
	v_and_b32_e32 v169, 0xffff0000, v47
	v_pk_add_f32 v[146:147], v[146:147], v[154:155]
	v_pk_add_f32 v[148:149], v[148:149], v[156:157]
	v_pk_add_f32 v[150:151], v[150:151], v[158:159]
	v_pk_add_f32 v[152:153], v[152:153], v[160:161]
	v_pk_mul_f32 v[170:171], v[162:163], v[162:163]
	v_pk_mul_f32 v[172:173], v[164:165], v[164:165]
	v_pk_mul_f32 v[174:175], v[166:167], v[166:167]
	v_pk_mul_f32 v[176:177], v[168:169], v[168:169]
	v_pk_fma_f32 v[170:171], v[170:171], v[140:141], v[142:143] op_sel_hi:[1,0,0]
	v_pk_fma_f32 v[172:173], v[172:173], v[140:141], v[142:143] op_sel_hi:[1,0,0]
	v_pk_fma_f32 v[174:175], v[174:175], v[140:141], v[142:143] op_sel_hi:[1,0,0]
	v_pk_fma_f32 v[176:177], v[176:177], v[140:141], v[142:143] op_sel_hi:[1,0,0]
	v_pk_mul_f32 v[170:171], v[170:171], v[162:163]
	v_pk_mul_f32 v[172:173], v[172:173], v[164:165]
	v_pk_mul_f32 v[174:175], v[174:175], v[166:167]
	v_pk_mul_f32 v[176:177], v[176:177], v[168:169]
	v_pk_mul_f32 v[154:155], v[146:147], v[162:163]
	v_pk_mul_f32 v[156:157], v[148:149], v[164:165]
	v_pk_mul_f32 v[158:159], v[150:151], v[166:167]
	v_pk_mul_f32 v[160:161], v[152:153], v[168:169]
	v_exp_f32_e32 v170, v170
	v_exp_f32_e32 v171, v171
	v_exp_f32_e32 v172, v172
	v_exp_f32_e32 v173, v173
	v_exp_f32_e32 v174, v174
	v_exp_f32_e32 v175, v175
	v_exp_f32_e32 v176, v176
	v_exp_f32_e32 v177, v177
	v_pk_add_f32 v[170:171], v[170:171], 1.0 op_sel_hi:[1,0]
	v_pk_add_f32 v[172:173], v[172:173], 1.0 op_sel_hi:[1,0]
	v_pk_add_f32 v[174:175], v[174:175], 1.0 op_sel_hi:[1,0]
	v_pk_add_f32 v[176:177], v[176:177], 1.0 op_sel_hi:[1,0]
	v_rcp_f32_e32 v170, v170
	v_rcp_f32_e32 v171, v171
	v_rcp_f32_e32 v172, v172
	v_rcp_f32_e32 v173, v173
	v_rcp_f32_e32 v174, v174
	v_rcp_f32_e32 v175, v175
	v_rcp_f32_e32 v176, v176
	v_rcp_f32_e32 v177, v177
	v_pk_mul_f32 v[96:97], v[154:155], v[170:171]
	v_pk_mul_f32 v[98:99], v[156:157], v[172:173]
	v_pk_mul_f32 v[100:101], v[158:159], v[174:175]
	v_pk_mul_f32 v[102:103], v[160:161], v[176:177]
	v_pk_mul_f32 v[112:113], v[96:97], v[96:97]
	v_pk_mul_f32 v[114:115], v[98:99], v[98:99]
	v_pk_fma_f32 v[112:113], v[100:101], v[100:101], v[112:113]
	v_pk_fma_f32 v[114:115], v[102:103], v[102:103], v[114:115]
	v_pk_add_f32 v[112:113], v[112:113], v[114:115]
	v_add_f32_e32 v112, v112, v113
	v_pk_mul_f32 v[146:147], v[96:97], v[120:121]
	v_pk_mul_f32 v[148:149], v[98:99], v[122:123]
	v_add_f32_dpp v112, v112, v112 quad_perm:[1,0,3,2] row_mask:0xf bank_mask:0xf
	v_pk_mul_f32 v[150:151], v[100:101], v[124:125]
	v_pk_mul_f32 v[152:153], v[102:103], v[126:127]
	v_add_f32_dpp v112, v112, v112 quad_perm:[2,3,0,1] row_mask:0xf bank_mask:0xf
	s_nop 1
	v_add_f32_dpp v112, v112, v112 row_half_mirror row_mask:0xf bank_mask:0xf
	s_nop 1
	v_add_f32_dpp v112, v112, v112 row_mirror row_mask:0xf bank_mask:0xf
	s_nop 1
	v_readlane_b32 s98, v112, 0
	v_readlane_b32 s99, v112, 16
	v_readlane_b32 s100, v112, 32
	v_readlane_b32 vcc_lo, v112, 48
	s_nop 1
	v_mov_b32_e32 v113, s98
	v_add_f32_e32 v113, s99, v113
	v_add_f32_e32 v113, s100, v113
	v_add_f32_e32 v113, vcc_lo, v113
	v_fmamk_f32 v144, v113, 0x3b000000, v131
	v_rsq_f32_e32 v144, v144
	s_nop 0
	v_pk_mul_f32 v[146:147], v[146:147], v[144:145] op_sel_hi:[1,0]
	v_pk_mul_f32 v[148:149], v[148:149], v[144:145] op_sel_hi:[1,0]
	v_pk_mul_f32 v[150:151], v[150:151], v[144:145] op_sel_hi:[1,0]
	v_pk_mul_f32 v[152:153], v[152:153], v[144:145] op_sel_hi:[1,0]
	v_cvt_pk_bf16_f32 v116, v146, v147
	v_cvt_pk_bf16_f32 v117, v148, v149
	v_cvt_pk_bf16_f32 v118, v150, v151
	v_cvt_pk_bf16_f32 v119, v152, v153
	v_add_u32_e32 v138, 0x2c00000, v135
	global_store_dwordx4 v138, v[116:119], s[34:35]
	s_waitcnt vmcnt(16)
	v_lshlrev_b32_e32 v146, 16, v48
	v_and_b32_e32 v147, 0xffff0000, v48
	v_lshlrev_b32_e32 v148, 16, v49
	v_and_b32_e32 v149, 0xffff0000, v49
	v_lshlrev_b32_e32 v150, 16, v50
	v_and_b32_e32 v151, 0xffff0000, v50
	v_lshlrev_b32_e32 v152, 16, v51
	v_and_b32_e32 v153, 0xffff0000, v51
	v_lshlrev_b32_e32 v154, 16, v52
	v_and_b32_e32 v155, 0xffff0000, v52
	v_lshlrev_b32_e32 v156, 16, v53
	v_and_b32_e32 v157, 0xffff0000, v53
	v_lshlrev_b32_e32 v158, 16, v54
	v_and_b32_e32 v159, 0xffff0000, v54
	v_lshlrev_b32_e32 v160, 16, v55
	v_and_b32_e32 v161, 0xffff0000, v55
	v_lshlrev_b32_e32 v162, 16, v56
	v_and_b32_e32 v163, 0xffff0000, v56
	v_lshlrev_b32_e32 v164, 16, v57
	v_and_b32_e32 v165, 0xffff0000, v57
	v_lshlrev_b32_e32 v166, 16, v58
	v_and_b32_e32 v167, 0xffff0000, v58
	v_lshlrev_b32_e32 v168, 16, v59
	v_and_b32_e32 v169, 0xffff0000, v59
	v_pk_add_f32 v[146:147], v[146:147], v[154:155]
	v_pk_add_f32 v[148:149], v[148:149], v[156:157]
	v_pk_add_f32 v[150:151], v[150:151], v[158:159]
	v_pk_add_f32 v[152:153], v[152:153], v[160:161]
	v_pk_mul_f32 v[170:171], v[162:163], v[162:163]
	v_pk_mul_f32 v[172:173], v[164:165], v[164:165]
	v_pk_mul_f32 v[174:175], v[166:167], v[166:167]
	v_pk_mul_f32 v[176:177], v[168:169], v[168:169]
	v_pk_fma_f32 v[170:171], v[170:171], v[140:141], v[142:143] op_sel_hi:[1,0,0]
	v_pk_fma_f32 v[172:173], v[172:173], v[140:141], v[142:143] op_sel_hi:[1,0,0]
	v_pk_fma_f32 v[174:175], v[174:175], v[140:141], v[142:143] op_sel_hi:[1,0,0]
	v_pk_fma_f32 v[176:177], v[176:177], v[140:141], v[142:143] op_sel_hi:[1,0,0]
	v_pk_mul_f32 v[170:171], v[170:171], v[162:163]
	v_pk_mul_f32 v[172:173], v[172:173], v[164:165]
	v_pk_mul_f32 v[174:175], v[174:175], v[166:167]
	v_pk_mul_f32 v[176:177], v[176:177], v[168:169]
	v_pk_mul_f32 v[154:155], v[146:147], v[162:163]
	v_pk_mul_f32 v[156:157], v[148:149], v[164:165]
	v_pk_mul_f32 v[158:159], v[150:151], v[166:167]
	v_pk_mul_f32 v[160:161], v[152:153], v[168:169]
	v_exp_f32_e32 v170, v170
	v_exp_f32_e32 v171, v171
	v_exp_f32_e32 v172, v172
	v_exp_f32_e32 v173, v173
	v_exp_f32_e32 v174, v174
	v_exp_f32_e32 v175, v175
	v_exp_f32_e32 v176, v176
	v_exp_f32_e32 v177, v177
	v_pk_add_f32 v[170:171], v[170:171], 1.0 op_sel_hi:[1,0]
	v_pk_add_f32 v[172:173], v[172:173], 1.0 op_sel_hi:[1,0]
	v_pk_add_f32 v[174:175], v[174:175], 1.0 op_sel_hi:[1,0]
	v_pk_add_f32 v[176:177], v[176:177], 1.0 op_sel_hi:[1,0]
	v_rcp_f32_e32 v170, v170
	v_rcp_f32_e32 v171, v171
	v_rcp_f32_e32 v172, v172
	v_rcp_f32_e32 v173, v173
	v_rcp_f32_e32 v174, v174
	v_rcp_f32_e32 v175, v175
	v_rcp_f32_e32 v176, v176
	v_rcp_f32_e32 v177, v177
	v_pk_mul_f32 v[96:97], v[154:155], v[170:171]
	v_pk_mul_f32 v[98:99], v[156:157], v[172:173]
	v_pk_mul_f32 v[100:101], v[158:159], v[174:175]
	v_pk_mul_f32 v[102:103], v[160:161], v[176:177]
	v_pk_mul_f32 v[112:113], v[96:97], v[96:97]
	v_pk_mul_f32 v[114:115], v[98:99], v[98:99]
	v_pk_fma_f32 v[112:113], v[100:101], v[100:101], v[112:113]
	v_pk_fma_f32 v[114:115], v[102:103], v[102:103], v[114:115]
	v_pk_add_f32 v[112:113], v[112:113], v[114:115]
	v_add_f32_e32 v112, v112, v113
	v_pk_mul_f32 v[146:147], v[96:97], v[120:121]
	v_pk_mul_f32 v[148:149], v[98:99], v[122:123]
	v_add_f32_dpp v112, v112, v112 quad_perm:[1,0,3,2] row_mask:0xf bank_mask:0xf
	v_pk_mul_f32 v[150:151], v[100:101], v[124:125]
	v_pk_mul_f32 v[152:153], v[102:103], v[126:127]
	v_add_f32_dpp v112, v112, v112 quad_perm:[2,3,0,1] row_mask:0xf bank_mask:0xf
	s_nop 1
	v_add_f32_dpp v112, v112, v112 row_half_mirror row_mask:0xf bank_mask:0xf
	s_nop 1
	v_add_f32_dpp v112, v112, v112 row_mirror row_mask:0xf bank_mask:0xf
	s_nop 1
	v_readlane_b32 s98, v112, 0
	v_readlane_b32 s99, v112, 16
	v_readlane_b32 s100, v112, 32
	v_readlane_b32 vcc_lo, v112, 48
	s_nop 1
	v_mov_b32_e32 v113, s98
	v_add_f32_e32 v113, s99, v113
	v_add_f32_e32 v113, s100, v113
	v_add_f32_e32 v113, vcc_lo, v113
	v_fmamk_f32 v144, v113, 0x3b000000, v131
	v_rsq_f32_e32 v144, v144
	s_nop 0
	v_pk_mul_f32 v[146:147], v[146:147], v[144:145] op_sel_hi:[1,0]
	v_pk_mul_f32 v[148:149], v[148:149], v[144:145] op_sel_hi:[1,0]
	v_pk_mul_f32 v[150:151], v[150:151], v[144:145] op_sel_hi:[1,0]
	v_pk_mul_f32 v[152:153], v[152:153], v[144:145] op_sel_hi:[1,0]
	v_cvt_pk_bf16_f32 v116, v146, v147
	v_cvt_pk_bf16_f32 v117, v148, v149
	v_cvt_pk_bf16_f32 v118, v150, v151
	v_cvt_pk_bf16_f32 v119, v152, v153
	v_add_u32_e32 v138, 0x3000000, v135
	global_store_dwordx4 v138, v[116:119], s[34:35]
	s_waitcnt vmcnt(13)
	v_lshlrev_b32_e32 v146, 16, v60
	v_and_b32_e32 v147, 0xffff0000, v60
	v_lshlrev_b32_e32 v148, 16, v61
	v_and_b32_e32 v149, 0xffff0000, v61
	v_lshlrev_b32_e32 v150, 16, v62
	v_and_b32_e32 v151, 0xffff0000, v62
	v_lshlrev_b32_e32 v152, 16, v63
	v_and_b32_e32 v153, 0xffff0000, v63
	v_lshlrev_b32_e32 v154, 16, v64
	v_and_b32_e32 v155, 0xffff0000, v64
	v_lshlrev_b32_e32 v156, 16, v65
	v_and_b32_e32 v157, 0xffff0000, v65
	v_lshlrev_b32_e32 v158, 16, v66
	v_and_b32_e32 v159, 0xffff0000, v66
	v_lshlrev_b32_e32 v160, 16, v67
	v_and_b32_e32 v161, 0xffff0000, v67
	v_lshlrev_b32_e32 v162, 16, v68
	v_and_b32_e32 v163, 0xffff0000, v68
	v_lshlrev_b32_e32 v164, 16, v69
	v_and_b32_e32 v165, 0xffff0000, v69
	v_lshlrev_b32_e32 v166, 16, v70
	v_and_b32_e32 v167, 0xffff0000, v70
	v_lshlrev_b32_e32 v168, 16, v71
	v_and_b32_e32 v169, 0xffff0000, v71
	v_pk_add_f32 v[146:147], v[146:147], v[154:155]
	v_pk_add_f32 v[148:149], v[148:149], v[156:157]
	v_pk_add_f32 v[150:151], v[150:151], v[158:159]
	v_pk_add_f32 v[152:153], v[152:153], v[160:161]
	v_pk_mul_f32 v[170:171], v[162:163], v[162:163]
	v_pk_mul_f32 v[172:173], v[164:165], v[164:165]
	v_pk_mul_f32 v[174:175], v[166:167], v[166:167]
	v_pk_mul_f32 v[176:177], v[168:169], v[168:169]
	v_pk_fma_f32 v[170:171], v[170:171], v[140:141], v[142:143] op_sel_hi:[1,0,0]
	v_pk_fma_f32 v[172:173], v[172:173], v[140:141], v[142:143] op_sel_hi:[1,0,0]
	v_pk_fma_f32 v[174:175], v[174:175], v[140:141], v[142:143] op_sel_hi:[1,0,0]
	v_pk_fma_f32 v[176:177], v[176:177], v[140:141], v[142:143] op_sel_hi:[1,0,0]
	v_pk_mul_f32 v[170:171], v[170:171], v[162:163]
	v_pk_mul_f32 v[172:173], v[172:173], v[164:165]
	v_pk_mul_f32 v[174:175], v[174:175], v[166:167]
	v_pk_mul_f32 v[176:177], v[176:177], v[168:169]
	v_pk_mul_f32 v[154:155], v[146:147], v[162:163]
	v_pk_mul_f32 v[156:157], v[148:149], v[164:165]
	v_pk_mul_f32 v[158:159], v[150:151], v[166:167]
	v_pk_mul_f32 v[160:161], v[152:153], v[168:169]
	v_exp_f32_e32 v170, v170
	v_exp_f32_e32 v171, v171
	v_exp_f32_e32 v172, v172
	v_exp_f32_e32 v173, v173
	v_exp_f32_e32 v174, v174
	v_exp_f32_e32 v175, v175
	v_exp_f32_e32 v176, v176
	v_exp_f32_e32 v177, v177
	v_pk_add_f32 v[170:171], v[170:171], 1.0 op_sel_hi:[1,0]
	v_pk_add_f32 v[172:173], v[172:173], 1.0 op_sel_hi:[1,0]
	v_pk_add_f32 v[174:175], v[174:175], 1.0 op_sel_hi:[1,0]
	v_pk_add_f32 v[176:177], v[176:177], 1.0 op_sel_hi:[1,0]
	v_rcp_f32_e32 v170, v170
	v_rcp_f32_e32 v171, v171
	v_rcp_f32_e32 v172, v172
	v_rcp_f32_e32 v173, v173
	v_rcp_f32_e32 v174, v174
	v_rcp_f32_e32 v175, v175
	v_rcp_f32_e32 v176, v176
	v_rcp_f32_e32 v177, v177
	v_pk_mul_f32 v[96:97], v[154:155], v[170:171]
	v_pk_mul_f32 v[98:99], v[156:157], v[172:173]
	v_pk_mul_f32 v[100:101], v[158:159], v[174:175]
	v_pk_mul_f32 v[102:103], v[160:161], v[176:177]
	v_pk_mul_f32 v[112:113], v[96:97], v[96:97]
	v_pk_mul_f32 v[114:115], v[98:99], v[98:99]
	v_pk_fma_f32 v[112:113], v[100:101], v[100:101], v[112:113]
	v_pk_fma_f32 v[114:115], v[102:103], v[102:103], v[114:115]
	v_pk_add_f32 v[112:113], v[112:113], v[114:115]
	v_add_f32_e32 v112, v112, v113
	v_pk_mul_f32 v[146:147], v[96:97], v[120:121]
	v_pk_mul_f32 v[148:149], v[98:99], v[122:123]
	v_add_f32_dpp v112, v112, v112 quad_perm:[1,0,3,2] row_mask:0xf bank_mask:0xf
	v_pk_mul_f32 v[150:151], v[100:101], v[124:125]
	v_pk_mul_f32 v[152:153], v[102:103], v[126:127]
	v_add_f32_dpp v112, v112, v112 quad_perm:[2,3,0,1] row_mask:0xf bank_mask:0xf
	s_nop 1
	v_add_f32_dpp v112, v112, v112 row_half_mirror row_mask:0xf bank_mask:0xf
	s_nop 1
	v_add_f32_dpp v112, v112, v112 row_mirror row_mask:0xf bank_mask:0xf
	s_nop 1
	v_readlane_b32 s98, v112, 0
	v_readlane_b32 s99, v112, 16
	v_readlane_b32 s100, v112, 32
	v_readlane_b32 vcc_lo, v112, 48
	s_nop 1
	v_mov_b32_e32 v113, s98
	v_add_f32_e32 v113, s99, v113
	v_add_f32_e32 v113, s100, v113
	v_add_f32_e32 v113, vcc_lo, v113
	v_fmamk_f32 v144, v113, 0x3b000000, v131
	v_rsq_f32_e32 v144, v144
	s_nop 0
	v_pk_mul_f32 v[146:147], v[146:147], v[144:145] op_sel_hi:[1,0]
	v_pk_mul_f32 v[148:149], v[148:149], v[144:145] op_sel_hi:[1,0]
	v_pk_mul_f32 v[150:151], v[150:151], v[144:145] op_sel_hi:[1,0]
	v_pk_mul_f32 v[152:153], v[152:153], v[144:145] op_sel_hi:[1,0]
	v_cvt_pk_bf16_f32 v116, v146, v147
	v_cvt_pk_bf16_f32 v117, v148, v149
	v_cvt_pk_bf16_f32 v118, v150, v151
	v_cvt_pk_bf16_f32 v119, v152, v153
	v_add_u32_e32 v138, 0x3400000, v135
	global_store_dwordx4 v138, v[116:119], s[34:35]
	s_waitcnt vmcnt(10)
	v_lshlrev_b32_e32 v146, 16, v72
	v_and_b32_e32 v147, 0xffff0000, v72
	v_lshlrev_b32_e32 v148, 16, v73
	v_and_b32_e32 v149, 0xffff0000, v73
	v_lshlrev_b32_e32 v150, 16, v74
	v_and_b32_e32 v151, 0xffff0000, v74
	v_lshlrev_b32_e32 v152, 16, v75
	v_and_b32_e32 v153, 0xffff0000, v75
	v_lshlrev_b32_e32 v154, 16, v76
	v_and_b32_e32 v155, 0xffff0000, v76
	v_lshlrev_b32_e32 v156, 16, v77
	v_and_b32_e32 v157, 0xffff0000, v77
	v_lshlrev_b32_e32 v158, 16, v78
	v_and_b32_e32 v159, 0xffff0000, v78
	v_lshlrev_b32_e32 v160, 16, v79
	v_and_b32_e32 v161, 0xffff0000, v79
	v_lshlrev_b32_e32 v162, 16, v80
	v_and_b32_e32 v163, 0xffff0000, v80
	v_lshlrev_b32_e32 v164, 16, v81
	v_and_b32_e32 v165, 0xffff0000, v81
	v_lshlrev_b32_e32 v166, 16, v82
	v_and_b32_e32 v167, 0xffff0000, v82
	v_lshlrev_b32_e32 v168, 16, v83
	v_and_b32_e32 v169, 0xffff0000, v83
	v_pk_add_f32 v[146:147], v[146:147], v[154:155]
	v_pk_add_f32 v[148:149], v[148:149], v[156:157]
	v_pk_add_f32 v[150:151], v[150:151], v[158:159]
	v_pk_add_f32 v[152:153], v[152:153], v[160:161]
	v_pk_mul_f32 v[170:171], v[162:163], v[162:163]
	v_pk_mul_f32 v[172:173], v[164:165], v[164:165]
	v_pk_mul_f32 v[174:175], v[166:167], v[166:167]
	v_pk_mul_f32 v[176:177], v[168:169], v[168:169]
	v_pk_fma_f32 v[170:171], v[170:171], v[140:141], v[142:143] op_sel_hi:[1,0,0]
	v_pk_fma_f32 v[172:173], v[172:173], v[140:141], v[142:143] op_sel_hi:[1,0,0]
	v_pk_fma_f32 v[174:175], v[174:175], v[140:141], v[142:143] op_sel_hi:[1,0,0]
	v_pk_fma_f32 v[176:177], v[176:177], v[140:141], v[142:143] op_sel_hi:[1,0,0]
	v_pk_mul_f32 v[170:171], v[170:171], v[162:163]
	v_pk_mul_f32 v[172:173], v[172:173], v[164:165]
	v_pk_mul_f32 v[174:175], v[174:175], v[166:167]
	v_pk_mul_f32 v[176:177], v[176:177], v[168:169]
	v_pk_mul_f32 v[154:155], v[146:147], v[162:163]
	v_pk_mul_f32 v[156:157], v[148:149], v[164:165]
	v_pk_mul_f32 v[158:159], v[150:151], v[166:167]
	v_pk_mul_f32 v[160:161], v[152:153], v[168:169]
	v_exp_f32_e32 v170, v170
	v_exp_f32_e32 v171, v171
	v_exp_f32_e32 v172, v172
	v_exp_f32_e32 v173, v173
	v_exp_f32_e32 v174, v174
	v_exp_f32_e32 v175, v175
	v_exp_f32_e32 v176, v176
	v_exp_f32_e32 v177, v177
	v_pk_add_f32 v[170:171], v[170:171], 1.0 op_sel_hi:[1,0]
	v_pk_add_f32 v[172:173], v[172:173], 1.0 op_sel_hi:[1,0]
	v_pk_add_f32 v[174:175], v[174:175], 1.0 op_sel_hi:[1,0]
	v_pk_add_f32 v[176:177], v[176:177], 1.0 op_sel_hi:[1,0]
	v_rcp_f32_e32 v170, v170
	v_rcp_f32_e32 v171, v171
	v_rcp_f32_e32 v172, v172
	v_rcp_f32_e32 v173, v173
	v_rcp_f32_e32 v174, v174
	v_rcp_f32_e32 v175, v175
	v_rcp_f32_e32 v176, v176
	v_rcp_f32_e32 v177, v177
	v_pk_mul_f32 v[96:97], v[154:155], v[170:171]
	v_pk_mul_f32 v[98:99], v[156:157], v[172:173]
	v_pk_mul_f32 v[100:101], v[158:159], v[174:175]
	v_pk_mul_f32 v[102:103], v[160:161], v[176:177]
	v_pk_mul_f32 v[112:113], v[96:97], v[96:97]
	v_pk_mul_f32 v[114:115], v[98:99], v[98:99]
	v_pk_fma_f32 v[112:113], v[100:101], v[100:101], v[112:113]
	v_pk_fma_f32 v[114:115], v[102:103], v[102:103], v[114:115]
	v_pk_add_f32 v[112:113], v[112:113], v[114:115]
	v_add_f32_e32 v112, v112, v113
	v_pk_mul_f32 v[146:147], v[96:97], v[120:121]
	v_pk_mul_f32 v[148:149], v[98:99], v[122:123]
	v_add_f32_dpp v112, v112, v112 quad_perm:[1,0,3,2] row_mask:0xf bank_mask:0xf
	v_pk_mul_f32 v[150:151], v[100:101], v[124:125]
	v_pk_mul_f32 v[152:153], v[102:103], v[126:127]
	v_add_f32_dpp v112, v112, v112 quad_perm:[2,3,0,1] row_mask:0xf bank_mask:0xf
	s_nop 1
	v_add_f32_dpp v112, v112, v112 row_half_mirror row_mask:0xf bank_mask:0xf
	s_nop 1
	v_add_f32_dpp v112, v112, v112 row_mirror row_mask:0xf bank_mask:0xf
	s_nop 1
	v_readlane_b32 s98, v112, 0
	v_readlane_b32 s99, v112, 16
	v_readlane_b32 s100, v112, 32
	v_readlane_b32 vcc_lo, v112, 48
	s_nop 1
	v_mov_b32_e32 v113, s98
	v_add_f32_e32 v113, s99, v113
	v_add_f32_e32 v113, s100, v113
	v_add_f32_e32 v113, vcc_lo, v113
	v_fmamk_f32 v144, v113, 0x3b000000, v131
	v_rsq_f32_e32 v144, v144
	s_nop 0
	v_pk_mul_f32 v[146:147], v[146:147], v[144:145] op_sel_hi:[1,0]
	v_pk_mul_f32 v[148:149], v[148:149], v[144:145] op_sel_hi:[1,0]
	v_pk_mul_f32 v[150:151], v[150:151], v[144:145] op_sel_hi:[1,0]
	v_pk_mul_f32 v[152:153], v[152:153], v[144:145] op_sel_hi:[1,0]
	v_cvt_pk_bf16_f32 v116, v146, v147
	v_cvt_pk_bf16_f32 v117, v148, v149
	v_cvt_pk_bf16_f32 v118, v150, v151
	v_cvt_pk_bf16_f32 v119, v152, v153
	v_add_u32_e32 v138, 0x3800000, v135
	global_store_dwordx4 v138, v[116:119], s[34:35]
	s_waitcnt vmcnt(7)
	v_lshlrev_b32_e32 v146, 16, v84
	v_and_b32_e32 v147, 0xffff0000, v84
	v_lshlrev_b32_e32 v148, 16, v85
	v_and_b32_e32 v149, 0xffff0000, v85
	v_lshlrev_b32_e32 v150, 16, v86
	v_and_b32_e32 v151, 0xffff0000, v86
	v_lshlrev_b32_e32 v152, 16, v87
	v_and_b32_e32 v153, 0xffff0000, v87
	v_lshlrev_b32_e32 v154, 16, v88
	v_and_b32_e32 v155, 0xffff0000, v88
	v_lshlrev_b32_e32 v156, 16, v89
	v_and_b32_e32 v157, 0xffff0000, v89
	v_lshlrev_b32_e32 v158, 16, v90
	v_and_b32_e32 v159, 0xffff0000, v90
	v_lshlrev_b32_e32 v160, 16, v91
	v_and_b32_e32 v161, 0xffff0000, v91
	v_lshlrev_b32_e32 v162, 16, v92
	v_and_b32_e32 v163, 0xffff0000, v92
	v_lshlrev_b32_e32 v164, 16, v93
	v_and_b32_e32 v165, 0xffff0000, v93
	v_lshlrev_b32_e32 v166, 16, v94
	v_and_b32_e32 v167, 0xffff0000, v94
	v_lshlrev_b32_e32 v168, 16, v95
	v_and_b32_e32 v169, 0xffff0000, v95
	v_pk_add_f32 v[146:147], v[146:147], v[154:155]
	v_pk_add_f32 v[148:149], v[148:149], v[156:157]
	v_pk_add_f32 v[150:151], v[150:151], v[158:159]
	v_pk_add_f32 v[152:153], v[152:153], v[160:161]
	v_pk_mul_f32 v[170:171], v[162:163], v[162:163]
	v_pk_mul_f32 v[172:173], v[164:165], v[164:165]
	v_pk_mul_f32 v[174:175], v[166:167], v[166:167]
	v_pk_mul_f32 v[176:177], v[168:169], v[168:169]
	v_pk_fma_f32 v[170:171], v[170:171], v[140:141], v[142:143] op_sel_hi:[1,0,0]
	v_pk_fma_f32 v[172:173], v[172:173], v[140:141], v[142:143] op_sel_hi:[1,0,0]
	v_pk_fma_f32 v[174:175], v[174:175], v[140:141], v[142:143] op_sel_hi:[1,0,0]
	v_pk_fma_f32 v[176:177], v[176:177], v[140:141], v[142:143] op_sel_hi:[1,0,0]
	v_pk_mul_f32 v[170:171], v[170:171], v[162:163]
	v_pk_mul_f32 v[172:173], v[172:173], v[164:165]
	v_pk_mul_f32 v[174:175], v[174:175], v[166:167]
	v_pk_mul_f32 v[176:177], v[176:177], v[168:169]
	v_pk_mul_f32 v[154:155], v[146:147], v[162:163]
	v_pk_mul_f32 v[156:157], v[148:149], v[164:165]
	v_pk_mul_f32 v[158:159], v[150:151], v[166:167]
	v_pk_mul_f32 v[160:161], v[152:153], v[168:169]
	v_exp_f32_e32 v170, v170
	v_exp_f32_e32 v171, v171
	v_exp_f32_e32 v172, v172
	v_exp_f32_e32 v173, v173
	v_exp_f32_e32 v174, v174
	v_exp_f32_e32 v175, v175
	v_exp_f32_e32 v176, v176
	v_exp_f32_e32 v177, v177
	v_pk_add_f32 v[170:171], v[170:171], 1.0 op_sel_hi:[1,0]
	v_pk_add_f32 v[172:173], v[172:173], 1.0 op_sel_hi:[1,0]
	v_pk_add_f32 v[174:175], v[174:175], 1.0 op_sel_hi:[1,0]
	v_pk_add_f32 v[176:177], v[176:177], 1.0 op_sel_hi:[1,0]
	v_rcp_f32_e32 v170, v170
	v_rcp_f32_e32 v171, v171
	v_rcp_f32_e32 v172, v172
	v_rcp_f32_e32 v173, v173
	v_rcp_f32_e32 v174, v174
	v_rcp_f32_e32 v175, v175
	v_rcp_f32_e32 v176, v176
	v_rcp_f32_e32 v177, v177
	v_pk_mul_f32 v[96:97], v[154:155], v[170:171]
	v_pk_mul_f32 v[98:99], v[156:157], v[172:173]
	v_pk_mul_f32 v[100:101], v[158:159], v[174:175]
	v_pk_mul_f32 v[102:103], v[160:161], v[176:177]
	v_pk_mul_f32 v[112:113], v[96:97], v[96:97]
	v_pk_mul_f32 v[114:115], v[98:99], v[98:99]
	v_pk_fma_f32 v[112:113], v[100:101], v[100:101], v[112:113]
	v_pk_fma_f32 v[114:115], v[102:103], v[102:103], v[114:115]
	v_pk_add_f32 v[112:113], v[112:113], v[114:115]
	v_add_f32_e32 v112, v112, v113
	v_pk_mul_f32 v[146:147], v[96:97], v[120:121]
	v_pk_mul_f32 v[148:149], v[98:99], v[122:123]
	v_add_f32_dpp v112, v112, v112 quad_perm:[1,0,3,2] row_mask:0xf bank_mask:0xf
	v_pk_mul_f32 v[150:151], v[100:101], v[124:125]
	v_pk_mul_f32 v[152:153], v[102:103], v[126:127]
	v_add_f32_dpp v112, v112, v112 quad_perm:[2,3,0,1] row_mask:0xf bank_mask:0xf
	s_nop 1
	v_add_f32_dpp v112, v112, v112 row_half_mirror row_mask:0xf bank_mask:0xf
	s_nop 1
	v_add_f32_dpp v112, v112, v112 row_mirror row_mask:0xf bank_mask:0xf
	s_nop 1
	v_readlane_b32 s98, v112, 0
	v_readlane_b32 s99, v112, 16
	v_readlane_b32 s100, v112, 32
	v_readlane_b32 vcc_lo, v112, 48
	s_nop 1
	v_mov_b32_e32 v113, s98
	v_add_f32_e32 v113, s99, v113
	v_add_f32_e32 v113, s100, v113
	v_add_f32_e32 v113, vcc_lo, v113
	v_fmamk_f32 v144, v113, 0x3b000000, v131
	v_rsq_f32_e32 v144, v144
	s_nop 0
	v_pk_mul_f32 v[146:147], v[146:147], v[144:145] op_sel_hi:[1,0]
	v_pk_mul_f32 v[148:149], v[148:149], v[144:145] op_sel_hi:[1,0]
	v_pk_mul_f32 v[150:151], v[150:151], v[144:145] op_sel_hi:[1,0]
	v_pk_mul_f32 v[152:153], v[152:153], v[144:145] op_sel_hi:[1,0]
	v_cvt_pk_bf16_f32 v116, v146, v147
	v_cvt_pk_bf16_f32 v117, v148, v149
	v_cvt_pk_bf16_f32 v118, v150, v151
	v_cvt_pk_bf16_f32 v119, v152, v153
	v_add_u32_e32 v138, 0x3c00000, v135
	global_store_dwordx4 v138, v[116:119], s[34:35]
	s_cmp_eq_u32 s101, 0
	s_cbranch_scc1 .Lcomb_retA
	s_branch .Lcomb_retB

.LBB0_690:
	v_fmamk_f32 v200, v166, 0x3a800000, v151
	v_rsq_f32_e32 v145, v200
	v_pk_mul_f32 v[120:121], v[124:125], v[120:121]
	v_pk_mul_f32 v[122:123], v[126:127], v[122:123]
	v_pk_mul_f32 v[112:113], v[116:117], v[112:113]
	v_mul_f32_e32 v166, 0xbfb8aa3b, v145
	v_pk_mul_f32 v[168:169], v[166:167], v[124:125] op_sel_hi:[0,1]
	v_exp_f32_e32 v168, v168
	v_exp_f32_e32 v169, v169
	v_pk_mul_f32 v[124:125], v[166:167], v[126:127] op_sel_hi:[0,1]
	v_exp_f32_e32 v124, v124
	v_exp_f32_e32 v125, v125
	v_pk_fma_f32 v[168:169], v[168:169], v[200:201], v[200:201] op_sel_hi:[1,0,0]
	v_rcp_f32_e32 v168, v168
	v_rcp_f32_e32 v169, v169
	v_pk_fma_f32 v[124:125], v[124:125], v[200:201], v[200:201] op_sel_hi:[1,0,0]
	v_pk_mul_f32 v[114:115], v[118:119], v[114:115]
	v_rcp_f32_e32 v124, v124
	v_rcp_f32_e32 v125, v125
	v_pk_mul_f32 v[120:121], v[168:169], v[120:121]
	v_pk_mul_f32 v[126:127], v[166:167], v[116:117] op_sel_hi:[0,1]
	v_exp_f32_e32 v126, v126
	v_exp_f32_e32 v127, v127
	v_pk_mul_f32 v[122:123], v[124:125], v[122:123]
	v_pk_mul_f32 v[124:125], v[166:167], v[118:119] op_sel_hi:[0,1]
	v_exp_f32_e32 v124, v124
	v_exp_f32_e32 v125, v125
	v_cvt_pk_bf16_f32 v120, v120, v121
	v_cvt_pk_bf16_f32 v121, v122, v123
	v_pk_fma_f32 v[122:123], v[126:127], v[200:201], v[200:201] op_sel_hi:[1,0,0]
	v_pk_fma_f32 v[116:117], v[124:125], v[200:201], v[200:201] op_sel_hi:[1,0,0]
	v_rcp_f32_e32 v122, v122
	v_rcp_f32_e32 v123, v123
	v_rcp_f32_e32 v116, v116
	v_rcp_f32_e32 v117, v117
	v_lshl_or_b32 v170, s18, 7, v148
	v_pk_mul_f32 v[112:113], v[122:123], v[112:113]
	v_lshl_add_u32 v144, s36, 8, v146
	v_cvt_pk_bf16_f32 v122, v112, v113
	v_pk_mul_f32 v[112:113], v[116:117], v[114:115]
	v_fmamk_f32 v202, v165, 0x3a800000, v151
	v_rsq_f32_e32 v119, v202
	v_ashrrev_i32_e32 v171, 31, v170
	v_cvt_pk_bf16_f32 v123, v112, v113
	v_mov_b64_e32 v[112:113], s[34:35]
	v_mul_f32_e32 v118, 0xbfb8aa3b, v119
	v_pk_mul_f32 v[124:125], v[118:119], v[108:109] op_sel_hi:[0,1]
	v_exp_f32_e32 v124, v124
	v_exp_f32_e32 v125, v125
	v_pk_mul_f32 v[104:105], v[108:109], v[104:105]
	v_pk_mul_f32 v[108:109], v[118:119], v[110:111] op_sel_hi:[0,1]
	v_mad_i64_i32 v[116:117], s[18:19], v144, s56, v[112:113]
	v_lshlrev_b64 v[114:115], 1, v[170:171]
	v_exp_f32_e32 v108, v108
	v_exp_f32_e32 v109, v109
	v_lshl_add_u64 v[216:217], v[116:117], 0, v[114:115]
	global_store_dwordx4 v[216:217], v[120:123], off
	s_mov_b32 s99, 0
	s_nop 0
	v_pk_fma_f32 v[108:109], v[108:109], v[202:203], v[202:203] op_sel_hi:[1,0,0]
	v_pk_fma_f32 v[120:121], v[124:125], v[202:203], v[202:203] op_sel_hi:[1,0,0]
	v_rcp_f32_e32 v108, v108
	v_rcp_f32_e32 v120, v120
	v_rcp_f32_e32 v121, v121
	v_rcp_f32_e32 v109, v109
	v_pk_mul_f32 v[106:107], v[110:111], v[106:107]
	v_pk_mul_f32 v[96:97], v[100:101], v[96:97]
	v_pk_mul_f32 v[104:105], v[120:121], v[104:105]
	v_pk_mul_f32 v[110:111], v[118:119], v[100:101] op_sel_hi:[0,1]
	v_exp_f32_e32 v110, v110
	v_exp_f32_e32 v111, v111
	v_pk_mul_f32 v[106:107], v[108:109], v[106:107]
	v_pk_mul_f32 v[108:109], v[118:119], v[102:103] op_sel_hi:[0,1]
	v_exp_f32_e32 v108, v108
	v_exp_f32_e32 v109, v109
	v_cvt_pk_bf16_f32 v104, v104, v105
	v_cvt_pk_bf16_f32 v105, v106, v107
	v_pk_fma_f32 v[106:107], v[110:111], v[202:203], v[202:203] op_sel_hi:[1,0,0]
	v_pk_fma_f32 v[100:101], v[108:109], v[202:203], v[202:203] op_sel_hi:[1,0,0]
	v_rcp_f32_e32 v106, v106
	v_rcp_f32_e32 v107, v107
	v_rcp_f32_e32 v100, v100
	v_rcp_f32_e32 v101, v101
	v_pk_mul_f32 v[98:99], v[102:103], v[98:99]
	v_pk_mul_f32 v[96:97], v[106:107], v[96:97]
	v_pk_mul_f32 v[88:89], v[92:93], v[88:89]
	v_cvt_pk_bf16_f32 v106, v96, v97
	v_pk_mul_f32 v[96:97], v[100:101], v[98:99]
	v_pk_mul_f32 v[90:91], v[94:95], v[90:91]
	v_cvt_pk_bf16_f32 v107, v96, v97
	v_fmamk_f32 v204, v164, 0x3a800000, v151
	v_rsq_f32_e32 v99, v204
	s_nop 0
	v_mul_f32_e32 v98, 0xbfb8aa3b, v99
	v_pk_mul_f32 v[100:101], v[98:99], v[92:93] op_sel_hi:[0,1]
	v_exp_f32_e32 v100, v100
	v_exp_f32_e32 v101, v101
	v_pk_mul_f32 v[92:93], v[98:99], v[94:95] op_sel_hi:[0,1]
	v_exp_f32_e32 v92, v92
	v_exp_f32_e32 v93, v93
	v_pk_fma_f32 v[100:101], v[100:101], v[204:205], v[204:205] op_sel_hi:[1,0,0]
	s_mov_b32 s98, 0x16000
	v_lshl_add_u64 v[96:97], v[216:217], 0, s[98:99]
	v_rcp_f32_e32 v100, v100
	v_rcp_f32_e32 v101, v101
	v_pk_fma_f32 v[92:93], v[92:93], v[204:205], v[204:205] op_sel_hi:[1,0,0]
	global_store_dwordx4 v[96:97], v[104:107], off
	v_rcp_f32_e32 v92, v92
	v_rcp_f32_e32 v93, v93
	v_pk_mul_f32 v[88:89], v[100:101], v[88:89]
	v_pk_mul_f32 v[94:95], v[98:99], v[84:85] op_sel_hi:[0,1]
	v_exp_f32_e32 v94, v94
	v_exp_f32_e32 v95, v95
	v_pk_mul_f32 v[90:91], v[92:93], v[90:91]
	v_pk_mul_f32 v[92:93], v[98:99], v[86:87] op_sel_hi:[0,1]
	v_exp_f32_e32 v92, v92
	v_exp_f32_e32 v93, v93
	v_cvt_pk_bf16_f32 v88, v88, v89
	v_cvt_pk_bf16_f32 v89, v90, v91
	v_pk_fma_f32 v[90:91], v[94:95], v[204:205], v[204:205] op_sel_hi:[1,0,0]
	v_pk_mul_f32 v[80:81], v[84:85], v[80:81]
	v_rcp_f32_e32 v90, v90
	v_rcp_f32_e32 v91, v91
	v_pk_fma_f32 v[84:85], v[92:93], v[204:205], v[204:205] op_sel_hi:[1,0,0]
	v_pk_mul_f32 v[82:83], v[86:87], v[82:83]
	v_rcp_f32_e32 v84, v84
	v_rcp_f32_e32 v85, v85
	v_pk_mul_f32 v[80:81], v[90:91], v[80:81]
	v_pk_mul_f32 v[72:73], v[76:77], v[72:73]
	v_cvt_pk_bf16_f32 v90, v80, v81
	v_pk_mul_f32 v[80:81], v[84:85], v[82:83]
	v_pk_mul_f32 v[74:75], v[78:79], v[74:75]
	v_cvt_pk_bf16_f32 v91, v80, v81
	v_fmamk_f32 v206, v163, 0x3a800000, v151
	v_rsq_f32_e32 v83, v206
	s_nop 0
	v_mul_f32_e32 v82, 0xbfb8aa3b, v83
	v_pk_mul_f32 v[84:85], v[82:83], v[76:77] op_sel_hi:[0,1]
	v_exp_f32_e32 v84, v84
	v_exp_f32_e32 v85, v85
	v_pk_mul_f32 v[76:77], v[82:83], v[78:79] op_sel_hi:[0,1]
	v_exp_f32_e32 v76, v76
	v_exp_f32_e32 v77, v77
	v_pk_fma_f32 v[84:85], v[84:85], v[206:207], v[206:207] op_sel_hi:[1,0,0]
	s_mov_b32 s98, 0x2c000
	v_lshl_add_u64 v[80:81], v[216:217], 0, s[98:99]
	v_rcp_f32_e32 v84, v84
	v_rcp_f32_e32 v85, v85
	v_pk_fma_f32 v[76:77], v[76:77], v[206:207], v[206:207] op_sel_hi:[1,0,0]
	global_store_dwordx4 v[80:81], v[88:91], off
	v_rcp_f32_e32 v76, v76
	v_rcp_f32_e32 v77, v77
	v_pk_mul_f32 v[72:73], v[84:85], v[72:73]
	v_pk_mul_f32 v[78:79], v[82:83], v[68:69] op_sel_hi:[0,1]
	v_exp_f32_e32 v78, v78
	v_exp_f32_e32 v79, v79
	v_pk_mul_f32 v[74:75], v[76:77], v[74:75]
	v_pk_mul_f32 v[76:77], v[82:83], v[70:71] op_sel_hi:[0,1]
	v_exp_f32_e32 v76, v76
	v_exp_f32_e32 v77, v77
	v_cvt_pk_bf16_f32 v72, v72, v73
	v_cvt_pk_bf16_f32 v73, v74, v75
	v_pk_fma_f32 v[74:75], v[78:79], v[206:207], v[206:207] op_sel_hi:[1,0,0]
	v_pk_mul_f32 v[64:65], v[68:69], v[64:65]
	v_rcp_f32_e32 v74, v74
	v_rcp_f32_e32 v75, v75
	v_pk_fma_f32 v[68:69], v[76:77], v[206:207], v[206:207] op_sel_hi:[1,0,0]
	v_pk_mul_f32 v[66:67], v[70:71], v[66:67]
	v_rcp_f32_e32 v68, v68
	v_rcp_f32_e32 v69, v69
	v_pk_mul_f32 v[64:65], v[74:75], v[64:65]
	v_pk_mul_f32 v[56:57], v[60:61], v[56:57]
	v_cvt_pk_bf16_f32 v74, v64, v65
	v_pk_mul_f32 v[64:65], v[68:69], v[66:67]
	v_pk_mul_f32 v[58:59], v[62:63], v[58:59]
	v_cvt_pk_bf16_f32 v75, v64, v65
	v_fmamk_f32 v208, v162, 0x3a800000, v151
	v_rsq_f32_e32 v67, v208
	s_nop 0
	v_mul_f32_e32 v66, 0xbfb8aa3b, v67
	v_pk_mul_f32 v[68:69], v[66:67], v[60:61] op_sel_hi:[0,1]
	v_exp_f32_e32 v68, v68
	v_exp_f32_e32 v69, v69
	v_pk_mul_f32 v[60:61], v[66:67], v[62:63] op_sel_hi:[0,1]
	v_exp_f32_e32 v60, v60
	v_exp_f32_e32 v61, v61
	v_pk_fma_f32 v[68:69], v[68:69], v[208:209], v[208:209] op_sel_hi:[1,0,0]
	s_mov_b32 s98, 0x42000
	v_lshl_add_u64 v[64:65], v[216:217], 0, s[98:99]
	v_rcp_f32_e32 v68, v68
	v_rcp_f32_e32 v69, v69
	v_pk_fma_f32 v[60:61], v[60:61], v[208:209], v[208:209] op_sel_hi:[1,0,0]
	global_store_dwordx4 v[64:65], v[72:75], off
	v_rcp_f32_e32 v60, v60
	v_rcp_f32_e32 v61, v61
	v_pk_mul_f32 v[56:57], v[68:69], v[56:57]
	v_pk_mul_f32 v[62:63], v[66:67], v[52:53] op_sel_hi:[0,1]
	v_exp_f32_e32 v62, v62
	v_exp_f32_e32 v63, v63
	v_pk_mul_f32 v[58:59], v[60:61], v[58:59]
	v_pk_mul_f32 v[60:61], v[66:67], v[54:55] op_sel_hi:[0,1]
	v_exp_f32_e32 v60, v60
	v_exp_f32_e32 v61, v61
	v_cvt_pk_bf16_f32 v56, v56, v57
	v_cvt_pk_bf16_f32 v57, v58, v59
	v_pk_fma_f32 v[58:59], v[62:63], v[208:209], v[208:209] op_sel_hi:[1,0,0]
	v_pk_mul_f32 v[48:49], v[52:53], v[48:49]
	v_rcp_f32_e32 v58, v58
	v_rcp_f32_e32 v59, v59
	v_pk_fma_f32 v[52:53], v[60:61], v[208:209], v[208:209] op_sel_hi:[1,0,0]
	v_pk_mul_f32 v[50:51], v[54:55], v[50:51]
	v_rcp_f32_e32 v52, v52
	v_rcp_f32_e32 v53, v53
	v_pk_mul_f32 v[48:49], v[58:59], v[48:49]
	v_pk_mul_f32 v[40:41], v[44:45], v[40:41]
	v_cvt_pk_bf16_f32 v58, v48, v49
	v_pk_mul_f32 v[48:49], v[52:53], v[50:51]
	v_fmamk_f32 v210, v161, 0x3a800000, v151
	v_rsq_f32_e32 v51, v210
	v_cvt_pk_bf16_f32 v59, v48, v49
	v_mul_f32_e32 v50, 0xbfb8aa3b, v51
	v_pk_mul_f32 v[52:53], v[50:51], v[44:45] op_sel_hi:[0,1]
	v_exp_f32_e32 v52, v52
	v_exp_f32_e32 v53, v53
	v_pk_mul_f32 v[44:45], v[50:51], v[46:47] op_sel_hi:[0,1]
	v_exp_f32_e32 v44, v44
	v_exp_f32_e32 v45, v45
	v_pk_fma_f32 v[52:53], v[52:53], v[210:211], v[210:211] op_sel_hi:[1,0,0]
	s_mov_b32 s98, 0xb0000
	v_lshl_add_u64 v[48:49], v[216:217], 0, s[98:99]
	v_rcp_f32_e32 v52, v52
	v_rcp_f32_e32 v53, v53
	v_pk_fma_f32 v[44:45], v[44:45], v[210:211], v[210:211] op_sel_hi:[1,0,0]
	global_store_dwordx4 v[48:49], v[56:59], off
	v_rcp_f32_e32 v44, v44
	v_rcp_f32_e32 v45, v45
	v_pk_mul_f32 v[42:43], v[46:47], v[42:43]
	v_pk_mul_f32 v[40:41], v[52:53], v[40:41]
	v_pk_mul_f32 v[46:47], v[50:51], v[36:37] op_sel_hi:[0,1]
	v_exp_f32_e32 v46, v46
	v_exp_f32_e32 v47, v47
	v_pk_mul_f32 v[42:43], v[44:45], v[42:43]
	v_pk_mul_f32 v[44:45], v[50:51], v[38:39] op_sel_hi:[0,1]
	v_exp_f32_e32 v44, v44
	v_exp_f32_e32 v45, v45
	v_cvt_pk_bf16_f32 v40, v40, v41
	v_cvt_pk_bf16_f32 v41, v42, v43
	v_pk_fma_f32 v[42:43], v[46:47], v[210:211], v[210:211] op_sel_hi:[1,0,0]
	v_pk_mul_f32 v[32:33], v[36:37], v[32:33]
	v_rcp_f32_e32 v42, v42
	v_rcp_f32_e32 v43, v43
	v_pk_fma_f32 v[36:37], v[44:45], v[210:211], v[210:211] op_sel_hi:[1,0,0]
	v_pk_mul_f32 v[34:35], v[38:39], v[34:35]
	v_rcp_f32_e32 v36, v36
	v_rcp_f32_e32 v37, v37
	v_pk_mul_f32 v[32:33], v[42:43], v[32:33]
	v_pk_mul_f32 v[24:25], v[28:29], v[24:25]
	v_cvt_pk_bf16_f32 v42, v32, v33
	v_pk_mul_f32 v[32:33], v[36:37], v[34:35]
	v_pk_mul_f32 v[26:27], v[30:31], v[26:27]
	v_cvt_pk_bf16_f32 v43, v32, v33
	v_fmamk_f32 v212, v152, 0x3a800000, v151
	v_rsq_f32_e32 v35, v212
	s_nop 0
	v_mul_f32_e32 v34, 0xbfb8aa3b, v35
	v_pk_mul_f32 v[36:37], v[34:35], v[28:29] op_sel_hi:[0,1]
	v_exp_f32_e32 v36, v36
	v_exp_f32_e32 v37, v37
	v_pk_mul_f32 v[28:29], v[34:35], v[30:31] op_sel_hi:[0,1]
	v_exp_f32_e32 v28, v28
	v_exp_f32_e32 v29, v29
	v_pk_fma_f32 v[36:37], v[36:37], v[212:213], v[212:213] op_sel_hi:[1,0,0]
	s_mov_b32 s98, 0xc6000
	v_lshl_add_u64 v[32:33], v[216:217], 0, s[98:99]
	v_rcp_f32_e32 v36, v36
	v_rcp_f32_e32 v37, v37
	v_pk_fma_f32 v[28:29], v[28:29], v[212:213], v[212:213] op_sel_hi:[1,0,0]
	global_store_dwordx4 v[32:33], v[40:43], off
	v_rcp_f32_e32 v28, v28
	v_rcp_f32_e32 v29, v29
	v_pk_mul_f32 v[24:25], v[36:37], v[24:25]
	v_pk_mul_f32 v[30:31], v[34:35], v[20:21] op_sel_hi:[0,1]
	v_exp_f32_e32 v30, v30
	v_exp_f32_e32 v31, v31
	v_pk_mul_f32 v[26:27], v[28:29], v[26:27]
	v_pk_mul_f32 v[28:29], v[34:35], v[22:23] op_sel_hi:[0,1]
	v_exp_f32_e32 v28, v28
	v_exp_f32_e32 v29, v29
	v_cvt_pk_bf16_f32 v24, v24, v25
	v_cvt_pk_bf16_f32 v25, v26, v27
	v_pk_fma_f32 v[26:27], v[30:31], v[212:213], v[212:213] op_sel_hi:[1,0,0]
	v_pk_mul_f32 v[16:17], v[20:21], v[16:17]
	v_rcp_f32_e32 v26, v26
	v_rcp_f32_e32 v27, v27
	v_pk_fma_f32 v[20:21], v[28:29], v[212:213], v[212:213] op_sel_hi:[1,0,0]
	v_pk_mul_f32 v[18:19], v[22:23], v[18:19]
	v_rcp_f32_e32 v20, v20
	v_rcp_f32_e32 v21, v21
	v_pk_mul_f32 v[16:17], v[26:27], v[16:17]
	v_pk_mul_f32 v[8:9], v[12:13], v[8:9]
	v_cvt_pk_bf16_f32 v26, v16, v17
	v_pk_mul_f32 v[16:17], v[20:21], v[18:19]
	v_pk_mul_f32 v[10:11], v[14:15], v[10:11]
	v_cvt_pk_bf16_f32 v27, v16, v17
	v_fmamk_f32 v214, v149, 0x3a800000, v151
	v_rsq_f32_e32 v19, v214
	s_nop 0
	v_mul_f32_e32 v18, 0xbfb8aa3b, v19
	v_pk_mul_f32 v[20:21], v[18:19], v[12:13] op_sel_hi:[0,1]
	v_exp_f32_e32 v20, v20
	v_exp_f32_e32 v21, v21
	v_pk_mul_f32 v[12:13], v[18:19], v[14:15] op_sel_hi:[0,1]
	v_exp_f32_e32 v12, v12
	v_exp_f32_e32 v13, v13
	v_pk_fma_f32 v[20:21], v[20:21], v[214:215], v[214:215] op_sel_hi:[1,0,0]
	s_mov_b32 s98, 0xdc000
	v_lshl_add_u64 v[16:17], v[216:217], 0, s[98:99]
	v_rcp_f32_e32 v20, v20
	v_rcp_f32_e32 v21, v21
	v_pk_fma_f32 v[12:13], v[12:13], v[214:215], v[214:215] op_sel_hi:[1,0,0]
	global_store_dwordx4 v[16:17], v[24:27], off
	v_rcp_f32_e32 v12, v12
	v_rcp_f32_e32 v13, v13
	v_pk_mul_f32 v[8:9], v[20:21], v[8:9]
	v_pk_mul_f32 v[14:15], v[18:19], v[4:5] op_sel_hi:[0,1]
	v_exp_f32_e32 v14, v14
	v_exp_f32_e32 v15, v15
	v_pk_mul_f32 v[10:11], v[12:13], v[10:11]
	v_pk_mul_f32 v[12:13], v[18:19], v[6:7] op_sel_hi:[0,1]
	v_exp_f32_e32 v12, v12
	v_exp_f32_e32 v13, v13
	v_cvt_pk_bf16_f32 v8, v8, v9
	v_cvt_pk_bf16_f32 v9, v10, v11
	v_pk_fma_f32 v[10:11], v[14:15], v[214:215], v[214:215] op_sel_hi:[1,0,0]
	v_pk_mul_f32 v[0:1], v[4:5], v[0:1]
	v_rcp_f32_e32 v10, v10
	v_rcp_f32_e32 v11, v11
	v_pk_fma_f32 v[4:5], v[12:13], v[214:215], v[214:215] op_sel_hi:[1,0,0]
	v_pk_mul_f32 v[2:3], v[6:7], v[2:3]
	v_rcp_f32_e32 v4, v4
	v_rcp_f32_e32 v5, v5
	v_pk_mul_f32 v[0:1], v[10:11], v[0:1]
	s_andn2_b64 vcc, exec, s[0:1]
	v_cvt_pk_bf16_f32 v10, v0, v1
	v_pk_mul_f32 v[0:1], v[4:5], v[2:3]
	s_mov_b64 s[0:1], -1
	v_cvt_pk_bf16_f32 v11, v0, v1
	s_mov_b32 s98, 0xf2000
	v_lshl_add_u64 v[0:1], v[216:217], 0, s[98:99]
	global_store_dwordx4 v[0:1], v[8:11], off
	s_cbranch_vccnz .LBB0_681
	s_andn2_b64 vcc, exec, s[6:7]
	s_cbranch_vccnz .LBB0_680
	s_barrier
	s_branch .LBB0_680
